# in-proj q/k epilogue rewritten by hand: rope tables loaded once per wave, packed-f32 rotation, SGPR-base store addressing (about 300 instead of 2000 instructions)
# speedup vs baseline: 1.0062x; 1.0059x over previous
.LBB0_829:
	s_andn2_b64 vcc, exec, s[8:9]
	s_cbranch_vccnz .LBB0_141
	s_waitcnt lgkmcnt(0)
	s_lshr_b32 s2, s17, 8
	s_and_b32 s3, s17, 0xff
	s_and_b32 s35, s19, 1
	s_lshr_b32 s7, s19, 1
	s_lshl_b32 s7, s7, 6
	s_lshl_b32 s38, s35, 5
	s_add_i32 s7, s7, s38
	s_and_b32 s34, s26, 1
	s_lshl_b32 s34, s34, 1
	s_cmp_gt_u32 s26, 1
	s_cbranch_scc1 .Lqk_disp_k
	s_cmp_eq_u32 s6, 0
	s_cbranch_scc1 .Lqk_q_c
	s_cmp_eq_u32 s35, 0
	s_cbranch_scc1 .Lqk_q_l0
	s_branch .Lqk_q_l1
.Lqk_disp_k:
	s_cmp_eq_u32 s6, 0
	s_cbranch_scc1 .Lqk_k_c
	s_cmp_eq_u32 s35, 0
	s_cbranch_scc1 .Lqk_k_l0
	s_branch .Lqk_k_l1
.Lqk_q_l0:
	v_lshlrev_b32_e32 v238, 3, v186
	v_lshl_add_u32 v236, v217, 10, v238
	s_add_u32 s10, s30, 0x629a000
	s_addc_u32 s11, s31, 0
	s_and_b32 s35, s2, 7
	s_lshl_b32 s35, s35, 2
	s_lshr_b32 s38, s3, 6
	s_add_i32 s35, s35, s38
	s_lshl_b32 s35, s35, 6
	s_add_u32 s10, s10, s35
	s_addc_u32 s11, s11, 0
	v_lshlrev_b32_e32 v241, 4, v186
	s_add_u32 s8, s10, 0x1000
	s_addc_u32 s9, s11, 0
	global_load_dwordx4 v[160:163], v241, s[10:11] offset:0
	global_load_dwordx4 v[164:167], v241, s[8:9] offset:0
	global_load_dwordx4 v[168:171], v241, s[10:11] offset:128
	global_load_dwordx4 v[172:175], v241, s[8:9] offset:128
	v_mov_b32_e32 v226, 0x3e38aa3b
	v_mov_b32_e32 v227, 0x3e38aa3b
	s_lshl_b32 s35, s17, 10
	s_lshl_b32 s38, s7, 1
	s_add_i32 s35, s35, s38
	s_lshl_b32 s38, s34, 8
	s_add_i32 s35, s35, s38
	s_add_u32 s12, s30, s35
	s_addc_u32 s13, s31, 0
	s_add_u32 s12, s12, 0xa2a4400
	s_addc_u32 s13, s13, 0
	s_waitcnt vmcnt(2)
	v_pk_mul_f32 v[160:161], v[160:161], v[226:227]
	v_pk_mul_f32 v[162:163], v[162:163], v[226:227]
	v_pk_mul_f32 v[164:165], v[164:165], v[226:227]
	v_pk_mul_f32 v[166:167], v[166:167], v[226:227]
	s_add_u32 s10, s12, 0x0
	s_addc_u32 s11, s13, 0
	v_pk_mul_f32 v[218:219], v[120:121], v[164:165]
	v_pk_mul_f32 v[220:221], v[122:123], v[166:167]
	v_pk_mul_f32 v[222:223], v[124:125], v[164:165]
	v_pk_mul_f32 v[224:225], v[126:127], v[166:167]
	v_pk_fma_f32 v[124:125], v[124:125], v[160:161], v[218:219] neg_lo:[0,0,1] neg_hi:[0,0,1]
	v_pk_fma_f32 v[126:127], v[126:127], v[162:163], v[220:221] neg_lo:[0,0,1] neg_hi:[0,0,1]
	v_pk_fma_f32 v[120:121], v[120:121], v[160:161], v[222:223]
	v_pk_fma_f32 v[122:123], v[122:123], v[162:163], v[224:225]
	v_cvt_pk_bf16_f32 v228, v124, v125
	v_cvt_pk_bf16_f32 v229, v126, v127
	v_cvt_pk_bf16_f32 v230, v120, v121
	v_cvt_pk_bf16_f32 v231, v122, v123
	global_store_dwordx2 v236, v[228:229], s[10:11] offset:0
	global_store_dwordx2 v236, v[230:231], s[10:11] offset:32
	v_pk_mul_f32 v[218:219], v[112:113], v[164:165]
	v_pk_mul_f32 v[220:221], v[114:115], v[166:167]
	v_pk_mul_f32 v[222:223], v[116:117], v[164:165]
	v_pk_mul_f32 v[224:225], v[118:119], v[166:167]
	v_pk_fma_f32 v[116:117], v[116:117], v[160:161], v[218:219] neg_lo:[0,0,1] neg_hi:[0,0,1]
	v_pk_fma_f32 v[118:119], v[118:119], v[162:163], v[220:221] neg_lo:[0,0,1] neg_hi:[0,0,1]
	v_pk_fma_f32 v[112:113], v[112:113], v[160:161], v[222:223]
	v_pk_fma_f32 v[114:115], v[114:115], v[162:163], v[224:225]
	v_cvt_pk_bf16_f32 v232, v116, v117
	v_cvt_pk_bf16_f32 v233, v118, v119
	v_cvt_pk_bf16_f32 v234, v112, v113
	v_cvt_pk_bf16_f32 v235, v114, v115
	global_store_dwordx2 v236, v[232:233], s[10:11] offset:256
	global_store_dwordx2 v236, v[234:235], s[10:11] offset:288
	s_add_u32 s10, s12, 0x4000
	s_addc_u32 s11, s13, 0
	v_pk_mul_f32 v[218:219], v[104:105], v[164:165]
	v_pk_mul_f32 v[220:221], v[106:107], v[166:167]
	v_pk_mul_f32 v[222:223], v[108:109], v[164:165]
	v_pk_mul_f32 v[224:225], v[110:111], v[166:167]
	v_pk_fma_f32 v[108:109], v[108:109], v[160:161], v[218:219] neg_lo:[0,0,1] neg_hi:[0,0,1]
	v_pk_fma_f32 v[110:111], v[110:111], v[162:163], v[220:221] neg_lo:[0,0,1] neg_hi:[0,0,1]
	v_pk_fma_f32 v[104:105], v[104:105], v[160:161], v[222:223]
	v_pk_fma_f32 v[106:107], v[106:107], v[162:163], v[224:225]
	v_cvt_pk_bf16_f32 v228, v108, v109
	v_cvt_pk_bf16_f32 v229, v110, v111
	v_cvt_pk_bf16_f32 v230, v104, v105
	v_cvt_pk_bf16_f32 v231, v106, v107
	global_store_dwordx2 v236, v[228:229], s[10:11] offset:0
	global_store_dwordx2 v236, v[230:231], s[10:11] offset:32
	v_pk_mul_f32 v[218:219], v[96:97], v[164:165]
	v_pk_mul_f32 v[220:221], v[98:99], v[166:167]
	v_pk_mul_f32 v[222:223], v[100:101], v[164:165]
	v_pk_mul_f32 v[224:225], v[102:103], v[166:167]
	v_pk_fma_f32 v[100:101], v[100:101], v[160:161], v[218:219] neg_lo:[0,0,1] neg_hi:[0,0,1]
	v_pk_fma_f32 v[102:103], v[102:103], v[162:163], v[220:221] neg_lo:[0,0,1] neg_hi:[0,0,1]
	v_pk_fma_f32 v[96:97], v[96:97], v[160:161], v[222:223]
	v_pk_fma_f32 v[98:99], v[98:99], v[162:163], v[224:225]
	v_cvt_pk_bf16_f32 v232, v100, v101
	v_cvt_pk_bf16_f32 v233, v102, v103
	v_cvt_pk_bf16_f32 v234, v96, v97
	v_cvt_pk_bf16_f32 v235, v98, v99
	global_store_dwordx2 v236, v[232:233], s[10:11] offset:256
	global_store_dwordx2 v236, v[234:235], s[10:11] offset:288
	s_add_u32 s10, s12, 0x8000
	s_addc_u32 s11, s13, 0
	v_pk_mul_f32 v[218:219], v[88:89], v[164:165]
	v_pk_mul_f32 v[220:221], v[90:91], v[166:167]
	v_pk_mul_f32 v[222:223], v[92:93], v[164:165]
	v_pk_mul_f32 v[224:225], v[94:95], v[166:167]
	v_pk_fma_f32 v[92:93], v[92:93], v[160:161], v[218:219] neg_lo:[0,0,1] neg_hi:[0,0,1]
	v_pk_fma_f32 v[94:95], v[94:95], v[162:163], v[220:221] neg_lo:[0,0,1] neg_hi:[0,0,1]
	v_pk_fma_f32 v[88:89], v[88:89], v[160:161], v[222:223]
	v_pk_fma_f32 v[90:91], v[90:91], v[162:163], v[224:225]
	v_cvt_pk_bf16_f32 v228, v92, v93
	v_cvt_pk_bf16_f32 v229, v94, v95
	v_cvt_pk_bf16_f32 v230, v88, v89
	v_cvt_pk_bf16_f32 v231, v90, v91
	global_store_dwordx2 v236, v[228:229], s[10:11] offset:0
	global_store_dwordx2 v236, v[230:231], s[10:11] offset:32
	v_pk_mul_f32 v[218:219], v[80:81], v[164:165]
	v_pk_mul_f32 v[220:221], v[82:83], v[166:167]
	v_pk_mul_f32 v[222:223], v[84:85], v[164:165]
	v_pk_mul_f32 v[224:225], v[86:87], v[166:167]
	v_pk_fma_f32 v[84:85], v[84:85], v[160:161], v[218:219] neg_lo:[0,0,1] neg_hi:[0,0,1]
	v_pk_fma_f32 v[86:87], v[86:87], v[162:163], v[220:221] neg_lo:[0,0,1] neg_hi:[0,0,1]
	v_pk_fma_f32 v[80:81], v[80:81], v[160:161], v[222:223]
	v_pk_fma_f32 v[82:83], v[82:83], v[162:163], v[224:225]
	v_cvt_pk_bf16_f32 v232, v84, v85
	v_cvt_pk_bf16_f32 v233, v86, v87
	v_cvt_pk_bf16_f32 v234, v80, v81
	v_cvt_pk_bf16_f32 v235, v82, v83
	global_store_dwordx2 v236, v[232:233], s[10:11] offset:256
	global_store_dwordx2 v236, v[234:235], s[10:11] offset:288
	s_add_u32 s10, s12, 0xc000
	s_addc_u32 s11, s13, 0
	v_pk_mul_f32 v[218:219], v[72:73], v[164:165]
	v_pk_mul_f32 v[220:221], v[74:75], v[166:167]
	v_pk_mul_f32 v[222:223], v[76:77], v[164:165]
	v_pk_mul_f32 v[224:225], v[78:79], v[166:167]
	v_pk_fma_f32 v[76:77], v[76:77], v[160:161], v[218:219] neg_lo:[0,0,1] neg_hi:[0,0,1]
	v_pk_fma_f32 v[78:79], v[78:79], v[162:163], v[220:221] neg_lo:[0,0,1] neg_hi:[0,0,1]
	v_pk_fma_f32 v[72:73], v[72:73], v[160:161], v[222:223]
	v_pk_fma_f32 v[74:75], v[74:75], v[162:163], v[224:225]
	v_cvt_pk_bf16_f32 v228, v76, v77
	v_cvt_pk_bf16_f32 v229, v78, v79
	v_cvt_pk_bf16_f32 v230, v72, v73
	v_cvt_pk_bf16_f32 v231, v74, v75
	global_store_dwordx2 v236, v[228:229], s[10:11] offset:0
	global_store_dwordx2 v236, v[230:231], s[10:11] offset:32
	v_pk_mul_f32 v[218:219], v[64:65], v[164:165]
	v_pk_mul_f32 v[220:221], v[66:67], v[166:167]
	v_pk_mul_f32 v[222:223], v[68:69], v[164:165]
	v_pk_mul_f32 v[224:225], v[70:71], v[166:167]
	v_pk_fma_f32 v[68:69], v[68:69], v[160:161], v[218:219] neg_lo:[0,0,1] neg_hi:[0,0,1]
	v_pk_fma_f32 v[70:71], v[70:71], v[162:163], v[220:221] neg_lo:[0,0,1] neg_hi:[0,0,1]
	v_pk_fma_f32 v[64:65], v[64:65], v[160:161], v[222:223]
	v_pk_fma_f32 v[66:67], v[66:67], v[162:163], v[224:225]
	v_cvt_pk_bf16_f32 v232, v68, v69
	v_cvt_pk_bf16_f32 v233, v70, v71
	v_cvt_pk_bf16_f32 v234, v64, v65
	v_cvt_pk_bf16_f32 v235, v66, v67
	global_store_dwordx2 v236, v[232:233], s[10:11] offset:256
	global_store_dwordx2 v236, v[234:235], s[10:11] offset:288
	s_waitcnt vmcnt(16)
	v_pk_mul_f32 v[168:169], v[168:169], v[226:227]
	v_pk_mul_f32 v[170:171], v[170:171], v[226:227]
	v_pk_mul_f32 v[172:173], v[172:173], v[226:227]
	v_pk_mul_f32 v[174:175], v[174:175], v[226:227]
	s_add_u32 s10, s12, 0x20000
	s_addc_u32 s11, s13, 0
	v_pk_mul_f32 v[218:219], v[56:57], v[172:173]
	v_pk_mul_f32 v[220:221], v[58:59], v[174:175]
	v_pk_mul_f32 v[222:223], v[60:61], v[172:173]
	v_pk_mul_f32 v[224:225], v[62:63], v[174:175]
	v_pk_fma_f32 v[60:61], v[60:61], v[168:169], v[218:219] neg_lo:[0,0,1] neg_hi:[0,0,1]
	v_pk_fma_f32 v[62:63], v[62:63], v[170:171], v[220:221] neg_lo:[0,0,1] neg_hi:[0,0,1]
	v_pk_fma_f32 v[56:57], v[56:57], v[168:169], v[222:223]
	v_pk_fma_f32 v[58:59], v[58:59], v[170:171], v[224:225]
	v_cvt_pk_bf16_f32 v228, v60, v61
	v_cvt_pk_bf16_f32 v229, v62, v63
	v_cvt_pk_bf16_f32 v230, v56, v57
	v_cvt_pk_bf16_f32 v231, v58, v59
	global_store_dwordx2 v236, v[228:229], s[10:11] offset:0
	global_store_dwordx2 v236, v[230:231], s[10:11] offset:32
	v_pk_mul_f32 v[218:219], v[48:49], v[172:173]
	v_pk_mul_f32 v[220:221], v[50:51], v[174:175]
	v_pk_mul_f32 v[222:223], v[52:53], v[172:173]
	v_pk_mul_f32 v[224:225], v[54:55], v[174:175]
	v_pk_fma_f32 v[52:53], v[52:53], v[168:169], v[218:219] neg_lo:[0,0,1] neg_hi:[0,0,1]
	v_pk_fma_f32 v[54:55], v[54:55], v[170:171], v[220:221] neg_lo:[0,0,1] neg_hi:[0,0,1]
	v_pk_fma_f32 v[48:49], v[48:49], v[168:169], v[222:223]
	v_pk_fma_f32 v[50:51], v[50:51], v[170:171], v[224:225]
	v_cvt_pk_bf16_f32 v232, v52, v53
	v_cvt_pk_bf16_f32 v233, v54, v55
	v_cvt_pk_bf16_f32 v234, v48, v49
	v_cvt_pk_bf16_f32 v235, v50, v51
	global_store_dwordx2 v236, v[232:233], s[10:11] offset:256
	global_store_dwordx2 v236, v[234:235], s[10:11] offset:288
	s_add_u32 s10, s12, 0x24000
	s_addc_u32 s11, s13, 0
	v_pk_mul_f32 v[218:219], v[40:41], v[172:173]
	v_pk_mul_f32 v[220:221], v[42:43], v[174:175]
	v_pk_mul_f32 v[222:223], v[44:45], v[172:173]
	v_pk_mul_f32 v[224:225], v[46:47], v[174:175]
	v_pk_fma_f32 v[44:45], v[44:45], v[168:169], v[218:219] neg_lo:[0,0,1] neg_hi:[0,0,1]
	v_pk_fma_f32 v[46:47], v[46:47], v[170:171], v[220:221] neg_lo:[0,0,1] neg_hi:[0,0,1]
	v_pk_fma_f32 v[40:41], v[40:41], v[168:169], v[222:223]
	v_pk_fma_f32 v[42:43], v[42:43], v[170:171], v[224:225]
	v_cvt_pk_bf16_f32 v228, v44, v45
	v_cvt_pk_bf16_f32 v229, v46, v47
	v_cvt_pk_bf16_f32 v230, v40, v41
	v_cvt_pk_bf16_f32 v231, v42, v43
	global_store_dwordx2 v236, v[228:229], s[10:11] offset:0
	global_store_dwordx2 v236, v[230:231], s[10:11] offset:32
	v_pk_mul_f32 v[218:219], v[32:33], v[172:173]
	v_pk_mul_f32 v[220:221], v[34:35], v[174:175]
	v_pk_mul_f32 v[222:223], v[36:37], v[172:173]
	v_pk_mul_f32 v[224:225], v[38:39], v[174:175]
	v_pk_fma_f32 v[36:37], v[36:37], v[168:169], v[218:219] neg_lo:[0,0,1] neg_hi:[0,0,1]
	v_pk_fma_f32 v[38:39], v[38:39], v[170:171], v[220:221] neg_lo:[0,0,1] neg_hi:[0,0,1]
	v_pk_fma_f32 v[32:33], v[32:33], v[168:169], v[222:223]
	v_pk_fma_f32 v[34:35], v[34:35], v[170:171], v[224:225]
	v_cvt_pk_bf16_f32 v232, v36, v37
	v_cvt_pk_bf16_f32 v233, v38, v39
	v_cvt_pk_bf16_f32 v234, v32, v33
	v_cvt_pk_bf16_f32 v235, v34, v35
	global_store_dwordx2 v236, v[232:233], s[10:11] offset:256
	global_store_dwordx2 v236, v[234:235], s[10:11] offset:288
	s_add_u32 s10, s12, 0x28000
	s_addc_u32 s11, s13, 0
	v_pk_mul_f32 v[218:219], v[24:25], v[172:173]
	v_pk_mul_f32 v[220:221], v[26:27], v[174:175]
	v_pk_mul_f32 v[222:223], v[28:29], v[172:173]
	v_pk_mul_f32 v[224:225], v[30:31], v[174:175]
	v_pk_fma_f32 v[28:29], v[28:29], v[168:169], v[218:219] neg_lo:[0,0,1] neg_hi:[0,0,1]
	v_pk_fma_f32 v[30:31], v[30:31], v[170:171], v[220:221] neg_lo:[0,0,1] neg_hi:[0,0,1]
	v_pk_fma_f32 v[24:25], v[24:25], v[168:169], v[222:223]
	v_pk_fma_f32 v[26:27], v[26:27], v[170:171], v[224:225]
	v_cvt_pk_bf16_f32 v228, v28, v29
	v_cvt_pk_bf16_f32 v229, v30, v31
	v_cvt_pk_bf16_f32 v230, v24, v25
	v_cvt_pk_bf16_f32 v231, v26, v27
	global_store_dwordx2 v236, v[228:229], s[10:11] offset:0
	global_store_dwordx2 v236, v[230:231], s[10:11] offset:32
	v_pk_mul_f32 v[218:219], v[16:17], v[172:173]
	v_pk_mul_f32 v[220:221], v[18:19], v[174:175]
	v_pk_mul_f32 v[222:223], v[20:21], v[172:173]
	v_pk_mul_f32 v[224:225], v[22:23], v[174:175]
	v_pk_fma_f32 v[20:21], v[20:21], v[168:169], v[218:219] neg_lo:[0,0,1] neg_hi:[0,0,1]
	v_pk_fma_f32 v[22:23], v[22:23], v[170:171], v[220:221] neg_lo:[0,0,1] neg_hi:[0,0,1]
	v_pk_fma_f32 v[16:17], v[16:17], v[168:169], v[222:223]
	v_pk_fma_f32 v[18:19], v[18:19], v[170:171], v[224:225]
	v_cvt_pk_bf16_f32 v232, v20, v21
	v_cvt_pk_bf16_f32 v233, v22, v23
	v_cvt_pk_bf16_f32 v234, v16, v17
	v_cvt_pk_bf16_f32 v235, v18, v19
	global_store_dwordx2 v236, v[232:233], s[10:11] offset:256
	global_store_dwordx2 v236, v[234:235], s[10:11] offset:288
	s_add_u32 s10, s12, 0x2c000
	s_addc_u32 s11, s13, 0
	v_pk_mul_f32 v[218:219], v[8:9], v[172:173]
	v_pk_mul_f32 v[220:221], v[10:11], v[174:175]
	v_pk_mul_f32 v[222:223], v[12:13], v[172:173]
	v_pk_mul_f32 v[224:225], v[14:15], v[174:175]
	v_pk_fma_f32 v[12:13], v[12:13], v[168:169], v[218:219] neg_lo:[0,0,1] neg_hi:[0,0,1]
	v_pk_fma_f32 v[14:15], v[14:15], v[170:171], v[220:221] neg_lo:[0,0,1] neg_hi:[0,0,1]
	v_pk_fma_f32 v[8:9], v[8:9], v[168:169], v[222:223]
	v_pk_fma_f32 v[10:11], v[10:11], v[170:171], v[224:225]
	v_cvt_pk_bf16_f32 v228, v12, v13
	v_cvt_pk_bf16_f32 v229, v14, v15
	v_cvt_pk_bf16_f32 v230, v8, v9
	v_cvt_pk_bf16_f32 v231, v10, v11
	global_store_dwordx2 v236, v[228:229], s[10:11] offset:0
	global_store_dwordx2 v236, v[230:231], s[10:11] offset:32
	v_pk_mul_f32 v[218:219], v[0:1], v[172:173]
	v_pk_mul_f32 v[220:221], v[2:3], v[174:175]
	v_pk_mul_f32 v[222:223], v[4:5], v[172:173]
	v_pk_mul_f32 v[224:225], v[6:7], v[174:175]
	v_pk_fma_f32 v[4:5], v[4:5], v[168:169], v[218:219] neg_lo:[0,0,1] neg_hi:[0,0,1]
	v_pk_fma_f32 v[6:7], v[6:7], v[170:171], v[220:221] neg_lo:[0,0,1] neg_hi:[0,0,1]
	v_pk_fma_f32 v[0:1], v[0:1], v[168:169], v[222:223]
	v_pk_fma_f32 v[2:3], v[2:3], v[170:171], v[224:225]
	v_cvt_pk_bf16_f32 v232, v4, v5
	v_cvt_pk_bf16_f32 v233, v6, v7
	v_cvt_pk_bf16_f32 v234, v0, v1
	v_cvt_pk_bf16_f32 v235, v2, v3
	global_store_dwordx2 v236, v[232:233], s[10:11] offset:256
	global_store_dwordx2 v236, v[234:235], s[10:11] offset:288
	s_branch .LBB0_141
.Lqk_q_l1:
	v_lshlrev_b32_e32 v238, 3, v186
	v_lshl_add_u32 v236, v217, 10, v238
	s_add_u32 s10, s30, 0x629a000
	s_addc_u32 s11, s31, 0
	v_lshlrev_b32_e32 v238, 4, v186
	v_lshl_add_u32 v241, v217, 6, v238
	s_add_u32 s8, s10, 0x1000
	s_addc_u32 s9, s11, 0
	global_load_dwordx4 v[160:163], v241, s[10:11] offset:0
	global_load_dwordx4 v[164:167], v241, s[8:9] offset:0
	global_load_dwordx4 v[168:171], v241, s[10:11] offset:1024
	global_load_dwordx4 v[172:175], v241, s[8:9] offset:1024
	global_load_dwordx4 v[176:179], v241, s[10:11] offset:2048
	global_load_dwordx4 v[180:183], v241, s[8:9] offset:2048
	global_load_dwordx4 v[184:187], v241, s[10:11] offset:3072
	global_load_dwordx4 v[188:191], v241, s[8:9] offset:3072
	v_mov_b32_e32 v226, 0x3e38aa3b
	v_mov_b32_e32 v227, 0x3e38aa3b
	s_lshl_b32 s35, s17, 10
	s_lshl_b32 s38, s7, 1
	s_add_i32 s35, s35, s38
	s_lshl_b32 s38, s34, 8
	s_add_i32 s35, s35, s38
	s_add_u32 s12, s30, s35
	s_addc_u32 s13, s31, 0
	s_add_u32 s12, s12, 0xa2a4400
	s_addc_u32 s13, s13, 0
	s_waitcnt vmcnt(6)
	v_pk_mul_f32 v[160:161], v[160:161], v[226:227]
	v_pk_mul_f32 v[162:163], v[162:163], v[226:227]
	v_pk_mul_f32 v[164:165], v[164:165], v[226:227]
	v_pk_mul_f32 v[166:167], v[166:167], v[226:227]
	s_add_u32 s10, s12, 0x0
	s_addc_u32 s11, s13, 0
	v_pk_mul_f32 v[218:219], v[120:121], v[164:165]
	v_pk_mul_f32 v[220:221], v[122:123], v[166:167]
	v_pk_mul_f32 v[222:223], v[124:125], v[164:165]
	v_pk_mul_f32 v[224:225], v[126:127], v[166:167]
	v_pk_fma_f32 v[124:125], v[124:125], v[160:161], v[218:219] neg_lo:[0,0,1] neg_hi:[0,0,1]
	v_pk_fma_f32 v[126:127], v[126:127], v[162:163], v[220:221] neg_lo:[0,0,1] neg_hi:[0,0,1]
	v_pk_fma_f32 v[120:121], v[120:121], v[160:161], v[222:223]
	v_pk_fma_f32 v[122:123], v[122:123], v[162:163], v[224:225]
	v_cvt_pk_bf16_f32 v228, v124, v125
	v_cvt_pk_bf16_f32 v229, v126, v127
	v_cvt_pk_bf16_f32 v230, v120, v121
	v_cvt_pk_bf16_f32 v231, v122, v123
	global_store_dwordx2 v236, v[228:229], s[10:11] offset:0
	global_store_dwordx2 v236, v[230:231], s[10:11] offset:32
	v_pk_mul_f32 v[218:219], v[112:113], v[164:165]
	v_pk_mul_f32 v[220:221], v[114:115], v[166:167]
	v_pk_mul_f32 v[222:223], v[116:117], v[164:165]
	v_pk_mul_f32 v[224:225], v[118:119], v[166:167]
	v_pk_fma_f32 v[116:117], v[116:117], v[160:161], v[218:219] neg_lo:[0,0,1] neg_hi:[0,0,1]
	v_pk_fma_f32 v[118:119], v[118:119], v[162:163], v[220:221] neg_lo:[0,0,1] neg_hi:[0,0,1]
	v_pk_fma_f32 v[112:113], v[112:113], v[160:161], v[222:223]
	v_pk_fma_f32 v[114:115], v[114:115], v[162:163], v[224:225]
	v_cvt_pk_bf16_f32 v232, v116, v117
	v_cvt_pk_bf16_f32 v233, v118, v119
	v_cvt_pk_bf16_f32 v234, v112, v113
	v_cvt_pk_bf16_f32 v235, v114, v115
	global_store_dwordx2 v236, v[232:233], s[10:11] offset:256
	global_store_dwordx2 v236, v[234:235], s[10:11] offset:288
	s_waitcnt vmcnt(8)
	v_pk_mul_f32 v[168:169], v[168:169], v[226:227]
	v_pk_mul_f32 v[170:171], v[170:171], v[226:227]
	v_pk_mul_f32 v[172:173], v[172:173], v[226:227]
	v_pk_mul_f32 v[174:175], v[174:175], v[226:227]
	s_add_u32 s10, s12, 0x4000
	s_addc_u32 s11, s13, 0
	v_pk_mul_f32 v[218:219], v[104:105], v[172:173]
	v_pk_mul_f32 v[220:221], v[106:107], v[174:175]
	v_pk_mul_f32 v[222:223], v[108:109], v[172:173]
	v_pk_mul_f32 v[224:225], v[110:111], v[174:175]
	v_pk_fma_f32 v[108:109], v[108:109], v[168:169], v[218:219] neg_lo:[0,0,1] neg_hi:[0,0,1]
	v_pk_fma_f32 v[110:111], v[110:111], v[170:171], v[220:221] neg_lo:[0,0,1] neg_hi:[0,0,1]
	v_pk_fma_f32 v[104:105], v[104:105], v[168:169], v[222:223]
	v_pk_fma_f32 v[106:107], v[106:107], v[170:171], v[224:225]
	v_cvt_pk_bf16_f32 v228, v108, v109
	v_cvt_pk_bf16_f32 v229, v110, v111
	v_cvt_pk_bf16_f32 v230, v104, v105
	v_cvt_pk_bf16_f32 v231, v106, v107
	global_store_dwordx2 v236, v[228:229], s[10:11] offset:0
	global_store_dwordx2 v236, v[230:231], s[10:11] offset:32
	v_pk_mul_f32 v[218:219], v[96:97], v[172:173]
	v_pk_mul_f32 v[220:221], v[98:99], v[174:175]
	v_pk_mul_f32 v[222:223], v[100:101], v[172:173]
	v_pk_mul_f32 v[224:225], v[102:103], v[174:175]
	v_pk_fma_f32 v[100:101], v[100:101], v[168:169], v[218:219] neg_lo:[0,0,1] neg_hi:[0,0,1]
	v_pk_fma_f32 v[102:103], v[102:103], v[170:171], v[220:221] neg_lo:[0,0,1] neg_hi:[0,0,1]
	v_pk_fma_f32 v[96:97], v[96:97], v[168:169], v[222:223]
	v_pk_fma_f32 v[98:99], v[98:99], v[170:171], v[224:225]
	v_cvt_pk_bf16_f32 v232, v100, v101
	v_cvt_pk_bf16_f32 v233, v102, v103
	v_cvt_pk_bf16_f32 v234, v96, v97
	v_cvt_pk_bf16_f32 v235, v98, v99
	global_store_dwordx2 v236, v[232:233], s[10:11] offset:256
	global_store_dwordx2 v236, v[234:235], s[10:11] offset:288
	s_waitcnt vmcnt(10)
	v_pk_mul_f32 v[176:177], v[176:177], v[226:227]
	v_pk_mul_f32 v[178:179], v[178:179], v[226:227]
	v_pk_mul_f32 v[180:181], v[180:181], v[226:227]
	v_pk_mul_f32 v[182:183], v[182:183], v[226:227]
	s_add_u32 s10, s12, 0x8000
	s_addc_u32 s11, s13, 0
	v_pk_mul_f32 v[218:219], v[88:89], v[180:181]
	v_pk_mul_f32 v[220:221], v[90:91], v[182:183]
	v_pk_mul_f32 v[222:223], v[92:93], v[180:181]
	v_pk_mul_f32 v[224:225], v[94:95], v[182:183]
	v_pk_fma_f32 v[92:93], v[92:93], v[176:177], v[218:219] neg_lo:[0,0,1] neg_hi:[0,0,1]
	v_pk_fma_f32 v[94:95], v[94:95], v[178:179], v[220:221] neg_lo:[0,0,1] neg_hi:[0,0,1]
	v_pk_fma_f32 v[88:89], v[88:89], v[176:177], v[222:223]
	v_pk_fma_f32 v[90:91], v[90:91], v[178:179], v[224:225]
	v_cvt_pk_bf16_f32 v228, v92, v93
	v_cvt_pk_bf16_f32 v229, v94, v95
	v_cvt_pk_bf16_f32 v230, v88, v89
	v_cvt_pk_bf16_f32 v231, v90, v91
	global_store_dwordx2 v236, v[228:229], s[10:11] offset:0
	global_store_dwordx2 v236, v[230:231], s[10:11] offset:32
	v_pk_mul_f32 v[218:219], v[80:81], v[180:181]
	v_pk_mul_f32 v[220:221], v[82:83], v[182:183]
	v_pk_mul_f32 v[222:223], v[84:85], v[180:181]
	v_pk_mul_f32 v[224:225], v[86:87], v[182:183]
	v_pk_fma_f32 v[84:85], v[84:85], v[176:177], v[218:219] neg_lo:[0,0,1] neg_hi:[0,0,1]
	v_pk_fma_f32 v[86:87], v[86:87], v[178:179], v[220:221] neg_lo:[0,0,1] neg_hi:[0,0,1]
	v_pk_fma_f32 v[80:81], v[80:81], v[176:177], v[222:223]
	v_pk_fma_f32 v[82:83], v[82:83], v[178:179], v[224:225]
	v_cvt_pk_bf16_f32 v232, v84, v85
	v_cvt_pk_bf16_f32 v233, v86, v87
	v_cvt_pk_bf16_f32 v234, v80, v81
	v_cvt_pk_bf16_f32 v235, v82, v83
	global_store_dwordx2 v236, v[232:233], s[10:11] offset:256
	global_store_dwordx2 v236, v[234:235], s[10:11] offset:288
	s_waitcnt vmcnt(12)
	v_pk_mul_f32 v[184:185], v[184:185], v[226:227]
	v_pk_mul_f32 v[186:187], v[186:187], v[226:227]
	v_pk_mul_f32 v[188:189], v[188:189], v[226:227]
	v_pk_mul_f32 v[190:191], v[190:191], v[226:227]
	s_add_u32 s10, s12, 0xc000
	s_addc_u32 s11, s13, 0
	v_pk_mul_f32 v[218:219], v[72:73], v[188:189]
	v_pk_mul_f32 v[220:221], v[74:75], v[190:191]
	v_pk_mul_f32 v[222:223], v[76:77], v[188:189]
	v_pk_mul_f32 v[224:225], v[78:79], v[190:191]
	v_pk_fma_f32 v[76:77], v[76:77], v[184:185], v[218:219] neg_lo:[0,0,1] neg_hi:[0,0,1]
	v_pk_fma_f32 v[78:79], v[78:79], v[186:187], v[220:221] neg_lo:[0,0,1] neg_hi:[0,0,1]
	v_pk_fma_f32 v[72:73], v[72:73], v[184:185], v[222:223]
	v_pk_fma_f32 v[74:75], v[74:75], v[186:187], v[224:225]
	v_cvt_pk_bf16_f32 v228, v76, v77
	v_cvt_pk_bf16_f32 v229, v78, v79
	v_cvt_pk_bf16_f32 v230, v72, v73
	v_cvt_pk_bf16_f32 v231, v74, v75
	global_store_dwordx2 v236, v[228:229], s[10:11] offset:0
	global_store_dwordx2 v236, v[230:231], s[10:11] offset:32
	v_pk_mul_f32 v[218:219], v[64:65], v[188:189]
	v_pk_mul_f32 v[220:221], v[66:67], v[190:191]
	v_pk_mul_f32 v[222:223], v[68:69], v[188:189]
	v_pk_mul_f32 v[224:225], v[70:71], v[190:191]
	v_pk_fma_f32 v[68:69], v[68:69], v[184:185], v[218:219] neg_lo:[0,0,1] neg_hi:[0,0,1]
	v_pk_fma_f32 v[70:71], v[70:71], v[186:187], v[220:221] neg_lo:[0,0,1] neg_hi:[0,0,1]
	v_pk_fma_f32 v[64:65], v[64:65], v[184:185], v[222:223]
	v_pk_fma_f32 v[66:67], v[66:67], v[186:187], v[224:225]
	v_cvt_pk_bf16_f32 v232, v68, v69
	v_cvt_pk_bf16_f32 v233, v70, v71
	v_cvt_pk_bf16_f32 v234, v64, v65
	v_cvt_pk_bf16_f32 v235, v66, v67
	global_store_dwordx2 v236, v[232:233], s[10:11] offset:256
	global_store_dwordx2 v236, v[234:235], s[10:11] offset:288
	s_add_u32 s10, s12, 0x20000
	s_addc_u32 s11, s13, 0
	v_pk_mul_f32 v[218:219], v[56:57], v[164:165]
	v_pk_mul_f32 v[220:221], v[58:59], v[166:167]
	v_pk_mul_f32 v[222:223], v[60:61], v[164:165]
	v_pk_mul_f32 v[224:225], v[62:63], v[166:167]
	v_pk_fma_f32 v[60:61], v[60:61], v[160:161], v[218:219] neg_lo:[0,0,1] neg_hi:[0,0,1]
	v_pk_fma_f32 v[62:63], v[62:63], v[162:163], v[220:221] neg_lo:[0,0,1] neg_hi:[0,0,1]
	v_pk_fma_f32 v[56:57], v[56:57], v[160:161], v[222:223]
	v_pk_fma_f32 v[58:59], v[58:59], v[162:163], v[224:225]
	v_cvt_pk_bf16_f32 v228, v60, v61
	v_cvt_pk_bf16_f32 v229, v62, v63
	v_cvt_pk_bf16_f32 v230, v56, v57
	v_cvt_pk_bf16_f32 v231, v58, v59
	global_store_dwordx2 v236, v[228:229], s[10:11] offset:0
	global_store_dwordx2 v236, v[230:231], s[10:11] offset:32
	v_pk_mul_f32 v[218:219], v[48:49], v[164:165]
	v_pk_mul_f32 v[220:221], v[50:51], v[166:167]
	v_pk_mul_f32 v[222:223], v[52:53], v[164:165]
	v_pk_mul_f32 v[224:225], v[54:55], v[166:167]
	v_pk_fma_f32 v[52:53], v[52:53], v[160:161], v[218:219] neg_lo:[0,0,1] neg_hi:[0,0,1]
	v_pk_fma_f32 v[54:55], v[54:55], v[162:163], v[220:221] neg_lo:[0,0,1] neg_hi:[0,0,1]
	v_pk_fma_f32 v[48:49], v[48:49], v[160:161], v[222:223]
	v_pk_fma_f32 v[50:51], v[50:51], v[162:163], v[224:225]
	v_cvt_pk_bf16_f32 v232, v52, v53
	v_cvt_pk_bf16_f32 v233, v54, v55
	v_cvt_pk_bf16_f32 v234, v48, v49
	v_cvt_pk_bf16_f32 v235, v50, v51
	global_store_dwordx2 v236, v[232:233], s[10:11] offset:256
	global_store_dwordx2 v236, v[234:235], s[10:11] offset:288
	s_add_u32 s10, s12, 0x24000
	s_addc_u32 s11, s13, 0
	v_pk_mul_f32 v[218:219], v[40:41], v[172:173]
	v_pk_mul_f32 v[220:221], v[42:43], v[174:175]
	v_pk_mul_f32 v[222:223], v[44:45], v[172:173]
	v_pk_mul_f32 v[224:225], v[46:47], v[174:175]
	v_pk_fma_f32 v[44:45], v[44:45], v[168:169], v[218:219] neg_lo:[0,0,1] neg_hi:[0,0,1]
	v_pk_fma_f32 v[46:47], v[46:47], v[170:171], v[220:221] neg_lo:[0,0,1] neg_hi:[0,0,1]
	v_pk_fma_f32 v[40:41], v[40:41], v[168:169], v[222:223]
	v_pk_fma_f32 v[42:43], v[42:43], v[170:171], v[224:225]
	v_cvt_pk_bf16_f32 v228, v44, v45
	v_cvt_pk_bf16_f32 v229, v46, v47
	v_cvt_pk_bf16_f32 v230, v40, v41
	v_cvt_pk_bf16_f32 v231, v42, v43
	global_store_dwordx2 v236, v[228:229], s[10:11] offset:0
	global_store_dwordx2 v236, v[230:231], s[10:11] offset:32
	v_pk_mul_f32 v[218:219], v[32:33], v[172:173]
	v_pk_mul_f32 v[220:221], v[34:35], v[174:175]
	v_pk_mul_f32 v[222:223], v[36:37], v[172:173]
	v_pk_mul_f32 v[224:225], v[38:39], v[174:175]
	v_pk_fma_f32 v[36:37], v[36:37], v[168:169], v[218:219] neg_lo:[0,0,1] neg_hi:[0,0,1]
	v_pk_fma_f32 v[38:39], v[38:39], v[170:171], v[220:221] neg_lo:[0,0,1] neg_hi:[0,0,1]
	v_pk_fma_f32 v[32:33], v[32:33], v[168:169], v[222:223]
	v_pk_fma_f32 v[34:35], v[34:35], v[170:171], v[224:225]
	v_cvt_pk_bf16_f32 v232, v36, v37
	v_cvt_pk_bf16_f32 v233, v38, v39
	v_cvt_pk_bf16_f32 v234, v32, v33
	v_cvt_pk_bf16_f32 v235, v34, v35
	global_store_dwordx2 v236, v[232:233], s[10:11] offset:256
	global_store_dwordx2 v236, v[234:235], s[10:11] offset:288
	s_add_u32 s10, s12, 0x28000
	s_addc_u32 s11, s13, 0
	v_pk_mul_f32 v[218:219], v[24:25], v[180:181]
	v_pk_mul_f32 v[220:221], v[26:27], v[182:183]
	v_pk_mul_f32 v[222:223], v[28:29], v[180:181]
	v_pk_mul_f32 v[224:225], v[30:31], v[182:183]
	v_pk_fma_f32 v[28:29], v[28:29], v[176:177], v[218:219] neg_lo:[0,0,1] neg_hi:[0,0,1]
	v_pk_fma_f32 v[30:31], v[30:31], v[178:179], v[220:221] neg_lo:[0,0,1] neg_hi:[0,0,1]
	v_pk_fma_f32 v[24:25], v[24:25], v[176:177], v[222:223]
	v_pk_fma_f32 v[26:27], v[26:27], v[178:179], v[224:225]
	v_cvt_pk_bf16_f32 v228, v28, v29
	v_cvt_pk_bf16_f32 v229, v30, v31
	v_cvt_pk_bf16_f32 v230, v24, v25
	v_cvt_pk_bf16_f32 v231, v26, v27
	global_store_dwordx2 v236, v[228:229], s[10:11] offset:0
	global_store_dwordx2 v236, v[230:231], s[10:11] offset:32
	v_pk_mul_f32 v[218:219], v[16:17], v[180:181]
	v_pk_mul_f32 v[220:221], v[18:19], v[182:183]
	v_pk_mul_f32 v[222:223], v[20:21], v[180:181]
	v_pk_mul_f32 v[224:225], v[22:23], v[182:183]
	v_pk_fma_f32 v[20:21], v[20:21], v[176:177], v[218:219] neg_lo:[0,0,1] neg_hi:[0,0,1]
	v_pk_fma_f32 v[22:23], v[22:23], v[178:179], v[220:221] neg_lo:[0,0,1] neg_hi:[0,0,1]
	v_pk_fma_f32 v[16:17], v[16:17], v[176:177], v[222:223]
	v_pk_fma_f32 v[18:19], v[18:19], v[178:179], v[224:225]
	v_cvt_pk_bf16_f32 v232, v20, v21
	v_cvt_pk_bf16_f32 v233, v22, v23
	v_cvt_pk_bf16_f32 v234, v16, v17
	v_cvt_pk_bf16_f32 v235, v18, v19
	global_store_dwordx2 v236, v[232:233], s[10:11] offset:256
	global_store_dwordx2 v236, v[234:235], s[10:11] offset:288
	s_add_u32 s10, s12, 0x2c000
	s_addc_u32 s11, s13, 0
	v_pk_mul_f32 v[218:219], v[8:9], v[188:189]
	v_pk_mul_f32 v[220:221], v[10:11], v[190:191]
	v_pk_mul_f32 v[222:223], v[12:13], v[188:189]
	v_pk_mul_f32 v[224:225], v[14:15], v[190:191]
	v_pk_fma_f32 v[12:13], v[12:13], v[184:185], v[218:219] neg_lo:[0,0,1] neg_hi:[0,0,1]
	v_pk_fma_f32 v[14:15], v[14:15], v[186:187], v[220:221] neg_lo:[0,0,1] neg_hi:[0,0,1]
	v_pk_fma_f32 v[8:9], v[8:9], v[184:185], v[222:223]
	v_pk_fma_f32 v[10:11], v[10:11], v[186:187], v[224:225]
	v_cvt_pk_bf16_f32 v228, v12, v13
	v_cvt_pk_bf16_f32 v229, v14, v15
	v_cvt_pk_bf16_f32 v230, v8, v9
	v_cvt_pk_bf16_f32 v231, v10, v11
	global_store_dwordx2 v236, v[228:229], s[10:11] offset:0
	global_store_dwordx2 v236, v[230:231], s[10:11] offset:32
	v_pk_mul_f32 v[218:219], v[0:1], v[188:189]
	v_pk_mul_f32 v[220:221], v[2:3], v[190:191]
	v_pk_mul_f32 v[222:223], v[4:5], v[188:189]
	v_pk_mul_f32 v[224:225], v[6:7], v[190:191]
	v_pk_fma_f32 v[4:5], v[4:5], v[184:185], v[218:219] neg_lo:[0,0,1] neg_hi:[0,0,1]
	v_pk_fma_f32 v[6:7], v[6:7], v[186:187], v[220:221] neg_lo:[0,0,1] neg_hi:[0,0,1]
	v_pk_fma_f32 v[0:1], v[0:1], v[184:185], v[222:223]
	v_pk_fma_f32 v[2:3], v[2:3], v[186:187], v[224:225]
	v_cvt_pk_bf16_f32 v232, v4, v5
	v_cvt_pk_bf16_f32 v233, v6, v7
	v_cvt_pk_bf16_f32 v234, v0, v1
	v_cvt_pk_bf16_f32 v235, v2, v3
	global_store_dwordx2 v236, v[232:233], s[10:11] offset:256
	global_store_dwordx2 v236, v[234:235], s[10:11] offset:288
	s_branch .LBB0_141
.Lqk_q_c:
	v_lshlrev_b32_e32 v238, 3, v186
	v_lshl_add_u32 v236, v217, 10, v238
	v_mov_b32_e32 v226, 0x3e38aa3b
	v_mov_b32_e32 v227, 0x3e38aa3b
	s_lshl_b32 s35, s17, 10
	s_lshl_b32 s38, s7, 1
	s_add_i32 s35, s35, s38
	s_lshl_b32 s38, s34, 8
	s_add_i32 s35, s35, s38
	s_add_u32 s12, s30, s35
	s_addc_u32 s13, s31, 0
	s_add_u32 s12, s12, 0xa2a4400
	s_addc_u32 s13, s13, 0
	s_add_u32 s10, s12, 0x0
	s_addc_u32 s11, s13, 0
	v_pk_mul_f32 v[124:125], v[124:125], v[226:227]
	v_pk_mul_f32 v[126:127], v[126:127], v[226:227]
	v_pk_mul_f32 v[120:121], v[120:121], v[226:227]
	v_pk_mul_f32 v[122:123], v[122:123], v[226:227]
	v_cvt_pk_bf16_f32 v228, v124, v125
	v_cvt_pk_bf16_f32 v229, v126, v127
	v_cvt_pk_bf16_f32 v230, v120, v121
	v_cvt_pk_bf16_f32 v231, v122, v123
	global_store_dwordx2 v236, v[228:229], s[10:11] offset:0
	global_store_dwordx2 v236, v[230:231], s[10:11] offset:32
	v_pk_mul_f32 v[116:117], v[116:117], v[226:227]
	v_pk_mul_f32 v[118:119], v[118:119], v[226:227]
	v_pk_mul_f32 v[112:113], v[112:113], v[226:227]
	v_pk_mul_f32 v[114:115], v[114:115], v[226:227]
	v_cvt_pk_bf16_f32 v232, v116, v117
	v_cvt_pk_bf16_f32 v233, v118, v119
	v_cvt_pk_bf16_f32 v234, v112, v113
	v_cvt_pk_bf16_f32 v235, v114, v115
	global_store_dwordx2 v236, v[232:233], s[10:11] offset:256
	global_store_dwordx2 v236, v[234:235], s[10:11] offset:288
	s_add_u32 s10, s12, 0x4000
	s_addc_u32 s11, s13, 0
	v_pk_mul_f32 v[108:109], v[108:109], v[226:227]
	v_pk_mul_f32 v[110:111], v[110:111], v[226:227]
	v_pk_mul_f32 v[104:105], v[104:105], v[226:227]
	v_pk_mul_f32 v[106:107], v[106:107], v[226:227]
	v_cvt_pk_bf16_f32 v228, v108, v109
	v_cvt_pk_bf16_f32 v229, v110, v111
	v_cvt_pk_bf16_f32 v230, v104, v105
	v_cvt_pk_bf16_f32 v231, v106, v107
	global_store_dwordx2 v236, v[228:229], s[10:11] offset:0
	global_store_dwordx2 v236, v[230:231], s[10:11] offset:32
	v_pk_mul_f32 v[100:101], v[100:101], v[226:227]
	v_pk_mul_f32 v[102:103], v[102:103], v[226:227]
	v_pk_mul_f32 v[96:97], v[96:97], v[226:227]
	v_pk_mul_f32 v[98:99], v[98:99], v[226:227]
	v_cvt_pk_bf16_f32 v232, v100, v101
	v_cvt_pk_bf16_f32 v233, v102, v103
	v_cvt_pk_bf16_f32 v234, v96, v97
	v_cvt_pk_bf16_f32 v235, v98, v99
	global_store_dwordx2 v236, v[232:233], s[10:11] offset:256
	global_store_dwordx2 v236, v[234:235], s[10:11] offset:288
	s_add_u32 s10, s12, 0x8000
	s_addc_u32 s11, s13, 0
	v_pk_mul_f32 v[92:93], v[92:93], v[226:227]
	v_pk_mul_f32 v[94:95], v[94:95], v[226:227]
	v_pk_mul_f32 v[88:89], v[88:89], v[226:227]
	v_pk_mul_f32 v[90:91], v[90:91], v[226:227]
	v_cvt_pk_bf16_f32 v228, v92, v93
	v_cvt_pk_bf16_f32 v229, v94, v95
	v_cvt_pk_bf16_f32 v230, v88, v89
	v_cvt_pk_bf16_f32 v231, v90, v91
	global_store_dwordx2 v236, v[228:229], s[10:11] offset:0
	global_store_dwordx2 v236, v[230:231], s[10:11] offset:32
	v_pk_mul_f32 v[84:85], v[84:85], v[226:227]
	v_pk_mul_f32 v[86:87], v[86:87], v[226:227]
	v_pk_mul_f32 v[80:81], v[80:81], v[226:227]
	v_pk_mul_f32 v[82:83], v[82:83], v[226:227]
	v_cvt_pk_bf16_f32 v232, v84, v85
	v_cvt_pk_bf16_f32 v233, v86, v87
	v_cvt_pk_bf16_f32 v234, v80, v81
	v_cvt_pk_bf16_f32 v235, v82, v83
	global_store_dwordx2 v236, v[232:233], s[10:11] offset:256
	global_store_dwordx2 v236, v[234:235], s[10:11] offset:288
	s_add_u32 s10, s12, 0xc000
	s_addc_u32 s11, s13, 0
	v_pk_mul_f32 v[76:77], v[76:77], v[226:227]
	v_pk_mul_f32 v[78:79], v[78:79], v[226:227]
	v_pk_mul_f32 v[72:73], v[72:73], v[226:227]
	v_pk_mul_f32 v[74:75], v[74:75], v[226:227]
	v_cvt_pk_bf16_f32 v228, v76, v77
	v_cvt_pk_bf16_f32 v229, v78, v79
	v_cvt_pk_bf16_f32 v230, v72, v73
	v_cvt_pk_bf16_f32 v231, v74, v75
	global_store_dwordx2 v236, v[228:229], s[10:11] offset:0
	global_store_dwordx2 v236, v[230:231], s[10:11] offset:32
	v_pk_mul_f32 v[68:69], v[68:69], v[226:227]
	v_pk_mul_f32 v[70:71], v[70:71], v[226:227]
	v_pk_mul_f32 v[64:65], v[64:65], v[226:227]
	v_pk_mul_f32 v[66:67], v[66:67], v[226:227]
	v_cvt_pk_bf16_f32 v232, v68, v69
	v_cvt_pk_bf16_f32 v233, v70, v71
	v_cvt_pk_bf16_f32 v234, v64, v65
	v_cvt_pk_bf16_f32 v235, v66, v67
	global_store_dwordx2 v236, v[232:233], s[10:11] offset:256
	global_store_dwordx2 v236, v[234:235], s[10:11] offset:288
	s_add_u32 s10, s12, 0x20000
	s_addc_u32 s11, s13, 0
	v_pk_mul_f32 v[60:61], v[60:61], v[226:227]
	v_pk_mul_f32 v[62:63], v[62:63], v[226:227]
	v_pk_mul_f32 v[56:57], v[56:57], v[226:227]
	v_pk_mul_f32 v[58:59], v[58:59], v[226:227]
	v_cvt_pk_bf16_f32 v228, v60, v61
	v_cvt_pk_bf16_f32 v229, v62, v63
	v_cvt_pk_bf16_f32 v230, v56, v57
	v_cvt_pk_bf16_f32 v231, v58, v59
	global_store_dwordx2 v236, v[228:229], s[10:11] offset:0
	global_store_dwordx2 v236, v[230:231], s[10:11] offset:32
	v_pk_mul_f32 v[52:53], v[52:53], v[226:227]
	v_pk_mul_f32 v[54:55], v[54:55], v[226:227]
	v_pk_mul_f32 v[48:49], v[48:49], v[226:227]
	v_pk_mul_f32 v[50:51], v[50:51], v[226:227]
	v_cvt_pk_bf16_f32 v232, v52, v53
	v_cvt_pk_bf16_f32 v233, v54, v55
	v_cvt_pk_bf16_f32 v234, v48, v49
	v_cvt_pk_bf16_f32 v235, v50, v51
	global_store_dwordx2 v236, v[232:233], s[10:11] offset:256
	global_store_dwordx2 v236, v[234:235], s[10:11] offset:288
	s_add_u32 s10, s12, 0x24000
	s_addc_u32 s11, s13, 0
	v_pk_mul_f32 v[44:45], v[44:45], v[226:227]
	v_pk_mul_f32 v[46:47], v[46:47], v[226:227]
	v_pk_mul_f32 v[40:41], v[40:41], v[226:227]
	v_pk_mul_f32 v[42:43], v[42:43], v[226:227]
	v_cvt_pk_bf16_f32 v228, v44, v45
	v_cvt_pk_bf16_f32 v229, v46, v47
	v_cvt_pk_bf16_f32 v230, v40, v41
	v_cvt_pk_bf16_f32 v231, v42, v43
	global_store_dwordx2 v236, v[228:229], s[10:11] offset:0
	global_store_dwordx2 v236, v[230:231], s[10:11] offset:32
	v_pk_mul_f32 v[36:37], v[36:37], v[226:227]
	v_pk_mul_f32 v[38:39], v[38:39], v[226:227]
	v_pk_mul_f32 v[32:33], v[32:33], v[226:227]
	v_pk_mul_f32 v[34:35], v[34:35], v[226:227]
	v_cvt_pk_bf16_f32 v232, v36, v37
	v_cvt_pk_bf16_f32 v233, v38, v39
	v_cvt_pk_bf16_f32 v234, v32, v33
	v_cvt_pk_bf16_f32 v235, v34, v35
	global_store_dwordx2 v236, v[232:233], s[10:11] offset:256
	global_store_dwordx2 v236, v[234:235], s[10:11] offset:288
	s_add_u32 s10, s12, 0x28000
	s_addc_u32 s11, s13, 0
	v_pk_mul_f32 v[28:29], v[28:29], v[226:227]
	v_pk_mul_f32 v[30:31], v[30:31], v[226:227]
	v_pk_mul_f32 v[24:25], v[24:25], v[226:227]
	v_pk_mul_f32 v[26:27], v[26:27], v[226:227]
	v_cvt_pk_bf16_f32 v228, v28, v29
	v_cvt_pk_bf16_f32 v229, v30, v31
	v_cvt_pk_bf16_f32 v230, v24, v25
	v_cvt_pk_bf16_f32 v231, v26, v27
	global_store_dwordx2 v236, v[228:229], s[10:11] offset:0
	global_store_dwordx2 v236, v[230:231], s[10:11] offset:32
	v_pk_mul_f32 v[20:21], v[20:21], v[226:227]
	v_pk_mul_f32 v[22:23], v[22:23], v[226:227]
	v_pk_mul_f32 v[16:17], v[16:17], v[226:227]
	v_pk_mul_f32 v[18:19], v[18:19], v[226:227]
	v_cvt_pk_bf16_f32 v232, v20, v21
	v_cvt_pk_bf16_f32 v233, v22, v23
	v_cvt_pk_bf16_f32 v234, v16, v17
	v_cvt_pk_bf16_f32 v235, v18, v19
	global_store_dwordx2 v236, v[232:233], s[10:11] offset:256
	global_store_dwordx2 v236, v[234:235], s[10:11] offset:288
	s_add_u32 s10, s12, 0x2c000
	s_addc_u32 s11, s13, 0
	v_pk_mul_f32 v[12:13], v[12:13], v[226:227]
	v_pk_mul_f32 v[14:15], v[14:15], v[226:227]
	v_pk_mul_f32 v[8:9], v[8:9], v[226:227]
	v_pk_mul_f32 v[10:11], v[10:11], v[226:227]
	v_cvt_pk_bf16_f32 v228, v12, v13
	v_cvt_pk_bf16_f32 v229, v14, v15
	v_cvt_pk_bf16_f32 v230, v8, v9
	v_cvt_pk_bf16_f32 v231, v10, v11
	global_store_dwordx2 v236, v[228:229], s[10:11] offset:0
	global_store_dwordx2 v236, v[230:231], s[10:11] offset:32
	v_pk_mul_f32 v[4:5], v[4:5], v[226:227]
	v_pk_mul_f32 v[6:7], v[6:7], v[226:227]
	v_pk_mul_f32 v[0:1], v[0:1], v[226:227]
	v_pk_mul_f32 v[2:3], v[2:3], v[226:227]
	v_cvt_pk_bf16_f32 v232, v4, v5
	v_cvt_pk_bf16_f32 v233, v6, v7
	v_cvt_pk_bf16_f32 v234, v0, v1
	v_cvt_pk_bf16_f32 v235, v2, v3
	global_store_dwordx2 v236, v[232:233], s[10:11] offset:256
	global_store_dwordx2 v236, v[234:235], s[10:11] offset:288
	s_branch .LBB0_141
.Lqk_k_l0:
	v_lshlrev_b32_e32 v238, 3, v186
	v_lshl_add_u32 v236, v217, 8, v238
	s_add_u32 s10, s30, 0x629a000
	s_addc_u32 s11, s31, 0
	s_and_b32 s35, s2, 7
	s_lshl_b32 s35, s35, 2
	s_lshr_b32 s38, s3, 6
	s_add_i32 s35, s35, s38
	s_lshl_b32 s35, s35, 6
	s_add_u32 s10, s10, s35
	s_addc_u32 s11, s11, 0
	v_lshlrev_b32_e32 v241, 4, v186
	s_add_u32 s8, s10, 0x1000
	s_addc_u32 s9, s11, 0
	global_load_dwordx4 v[160:163], v241, s[10:11] offset:0
	global_load_dwordx4 v[164:167], v241, s[8:9] offset:0
	global_load_dwordx4 v[168:171], v241, s[10:11] offset:128
	global_load_dwordx4 v[172:175], v241, s[8:9] offset:128
	s_add_i32 s35, s2, 0xffffffe0
	s_lshr_b32 s38, s35, 3
	s_lshl_b32 s38, s38, 2
	s_add_i32 s38, s38, s34
	s_mulk_i32 s38, 0xa00
	s_and_b32 s35, s35, 7
	s_lshl_b32 s35, s35, 8
	s_add_i32 s35, s35, s3
	s_add_i32 s35, s35, s38
	s_lshl_b32 s35, s35, 8
	s_lshl_b32 s38, s7, 1
	s_add_i32 s35, s35, s38
	s_add_u32 s12, s30, s35
	s_addc_u32 s13, s31, 0
	s_add_u32 s12, s12, 0xc2a4400
	s_addc_u32 s13, s13, 0
	s_waitcnt vmcnt(2)
	s_add_u32 s10, s12, 0x0
	s_addc_u32 s11, s13, 0
	v_pk_mul_f32 v[218:219], v[120:121], v[164:165]
	v_pk_mul_f32 v[220:221], v[122:123], v[166:167]
	v_pk_mul_f32 v[222:223], v[124:125], v[164:165]
	v_pk_mul_f32 v[224:225], v[126:127], v[166:167]
	v_pk_fma_f32 v[124:125], v[124:125], v[160:161], v[218:219] neg_lo:[0,0,1] neg_hi:[0,0,1]
	v_pk_fma_f32 v[126:127], v[126:127], v[162:163], v[220:221] neg_lo:[0,0,1] neg_hi:[0,0,1]
	v_pk_fma_f32 v[120:121], v[120:121], v[160:161], v[222:223]
	v_pk_fma_f32 v[122:123], v[122:123], v[162:163], v[224:225]
	v_cvt_pk_bf16_f32 v228, v124, v125
	v_cvt_pk_bf16_f32 v229, v126, v127
	v_cvt_pk_bf16_f32 v230, v120, v121
	v_cvt_pk_bf16_f32 v231, v122, v123
	global_store_dwordx2 v236, v[228:229], s[10:11] offset:0
	global_store_dwordx2 v236, v[230:231], s[10:11] offset:32
	s_add_u32 s10, s12, 0xa0000
	s_addc_u32 s11, s13, 0
	v_pk_mul_f32 v[218:219], v[112:113], v[164:165]
	v_pk_mul_f32 v[220:221], v[114:115], v[166:167]
	v_pk_mul_f32 v[222:223], v[116:117], v[164:165]
	v_pk_mul_f32 v[224:225], v[118:119], v[166:167]
	v_pk_fma_f32 v[116:117], v[116:117], v[160:161], v[218:219] neg_lo:[0,0,1] neg_hi:[0,0,1]
	v_pk_fma_f32 v[118:119], v[118:119], v[162:163], v[220:221] neg_lo:[0,0,1] neg_hi:[0,0,1]
	v_pk_fma_f32 v[112:113], v[112:113], v[160:161], v[222:223]
	v_pk_fma_f32 v[114:115], v[114:115], v[162:163], v[224:225]
	v_cvt_pk_bf16_f32 v232, v116, v117
	v_cvt_pk_bf16_f32 v233, v118, v119
	v_cvt_pk_bf16_f32 v234, v112, v113
	v_cvt_pk_bf16_f32 v235, v114, v115
	global_store_dwordx2 v236, v[232:233], s[10:11] offset:0
	global_store_dwordx2 v236, v[234:235], s[10:11] offset:32
	s_add_u32 s10, s12, 0x1000
	s_addc_u32 s11, s13, 0
	v_pk_mul_f32 v[218:219], v[104:105], v[164:165]
	v_pk_mul_f32 v[220:221], v[106:107], v[166:167]
	v_pk_mul_f32 v[222:223], v[108:109], v[164:165]
	v_pk_mul_f32 v[224:225], v[110:111], v[166:167]
	v_pk_fma_f32 v[108:109], v[108:109], v[160:161], v[218:219] neg_lo:[0,0,1] neg_hi:[0,0,1]
	v_pk_fma_f32 v[110:111], v[110:111], v[162:163], v[220:221] neg_lo:[0,0,1] neg_hi:[0,0,1]
	v_pk_fma_f32 v[104:105], v[104:105], v[160:161], v[222:223]
	v_pk_fma_f32 v[106:107], v[106:107], v[162:163], v[224:225]
	v_cvt_pk_bf16_f32 v228, v108, v109
	v_cvt_pk_bf16_f32 v229, v110, v111
	v_cvt_pk_bf16_f32 v230, v104, v105
	v_cvt_pk_bf16_f32 v231, v106, v107
	global_store_dwordx2 v236, v[228:229], s[10:11] offset:0
	global_store_dwordx2 v236, v[230:231], s[10:11] offset:32
	s_add_u32 s10, s12, 0xa1000
	s_addc_u32 s11, s13, 0
	v_pk_mul_f32 v[218:219], v[96:97], v[164:165]
	v_pk_mul_f32 v[220:221], v[98:99], v[166:167]
	v_pk_mul_f32 v[222:223], v[100:101], v[164:165]
	v_pk_mul_f32 v[224:225], v[102:103], v[166:167]
	v_pk_fma_f32 v[100:101], v[100:101], v[160:161], v[218:219] neg_lo:[0,0,1] neg_hi:[0,0,1]
	v_pk_fma_f32 v[102:103], v[102:103], v[162:163], v[220:221] neg_lo:[0,0,1] neg_hi:[0,0,1]
	v_pk_fma_f32 v[96:97], v[96:97], v[160:161], v[222:223]
	v_pk_fma_f32 v[98:99], v[98:99], v[162:163], v[224:225]
	v_cvt_pk_bf16_f32 v232, v100, v101
	v_cvt_pk_bf16_f32 v233, v102, v103
	v_cvt_pk_bf16_f32 v234, v96, v97
	v_cvt_pk_bf16_f32 v235, v98, v99
	global_store_dwordx2 v236, v[232:233], s[10:11] offset:0
	global_store_dwordx2 v236, v[234:235], s[10:11] offset:32
	s_add_u32 s10, s12, 0x2000
	s_addc_u32 s11, s13, 0
	v_pk_mul_f32 v[218:219], v[88:89], v[164:165]
	v_pk_mul_f32 v[220:221], v[90:91], v[166:167]
	v_pk_mul_f32 v[222:223], v[92:93], v[164:165]
	v_pk_mul_f32 v[224:225], v[94:95], v[166:167]
	v_pk_fma_f32 v[92:93], v[92:93], v[160:161], v[218:219] neg_lo:[0,0,1] neg_hi:[0,0,1]
	v_pk_fma_f32 v[94:95], v[94:95], v[162:163], v[220:221] neg_lo:[0,0,1] neg_hi:[0,0,1]
	v_pk_fma_f32 v[88:89], v[88:89], v[160:161], v[222:223]
	v_pk_fma_f32 v[90:91], v[90:91], v[162:163], v[224:225]
	v_cvt_pk_bf16_f32 v228, v92, v93
	v_cvt_pk_bf16_f32 v229, v94, v95
	v_cvt_pk_bf16_f32 v230, v88, v89
	v_cvt_pk_bf16_f32 v231, v90, v91
	global_store_dwordx2 v236, v[228:229], s[10:11] offset:0
	global_store_dwordx2 v236, v[230:231], s[10:11] offset:32
	s_add_u32 s10, s12, 0xa2000
	s_addc_u32 s11, s13, 0
	v_pk_mul_f32 v[218:219], v[80:81], v[164:165]
	v_pk_mul_f32 v[220:221], v[82:83], v[166:167]
	v_pk_mul_f32 v[222:223], v[84:85], v[164:165]
	v_pk_mul_f32 v[224:225], v[86:87], v[166:167]
	v_pk_fma_f32 v[84:85], v[84:85], v[160:161], v[218:219] neg_lo:[0,0,1] neg_hi:[0,0,1]
	v_pk_fma_f32 v[86:87], v[86:87], v[162:163], v[220:221] neg_lo:[0,0,1] neg_hi:[0,0,1]
	v_pk_fma_f32 v[80:81], v[80:81], v[160:161], v[222:223]
	v_pk_fma_f32 v[82:83], v[82:83], v[162:163], v[224:225]
	v_cvt_pk_bf16_f32 v232, v84, v85
	v_cvt_pk_bf16_f32 v233, v86, v87
	v_cvt_pk_bf16_f32 v234, v80, v81
	v_cvt_pk_bf16_f32 v235, v82, v83
	global_store_dwordx2 v236, v[232:233], s[10:11] offset:0
	global_store_dwordx2 v236, v[234:235], s[10:11] offset:32
	s_add_u32 s10, s12, 0x3000
	s_addc_u32 s11, s13, 0
	v_pk_mul_f32 v[218:219], v[72:73], v[164:165]
	v_pk_mul_f32 v[220:221], v[74:75], v[166:167]
	v_pk_mul_f32 v[222:223], v[76:77], v[164:165]
	v_pk_mul_f32 v[224:225], v[78:79], v[166:167]
	v_pk_fma_f32 v[76:77], v[76:77], v[160:161], v[218:219] neg_lo:[0,0,1] neg_hi:[0,0,1]
	v_pk_fma_f32 v[78:79], v[78:79], v[162:163], v[220:221] neg_lo:[0,0,1] neg_hi:[0,0,1]
	v_pk_fma_f32 v[72:73], v[72:73], v[160:161], v[222:223]
	v_pk_fma_f32 v[74:75], v[74:75], v[162:163], v[224:225]
	v_cvt_pk_bf16_f32 v228, v76, v77
	v_cvt_pk_bf16_f32 v229, v78, v79
	v_cvt_pk_bf16_f32 v230, v72, v73
	v_cvt_pk_bf16_f32 v231, v74, v75
	global_store_dwordx2 v236, v[228:229], s[10:11] offset:0
	global_store_dwordx2 v236, v[230:231], s[10:11] offset:32
	s_add_u32 s10, s12, 0xa3000
	s_addc_u32 s11, s13, 0
	v_pk_mul_f32 v[218:219], v[64:65], v[164:165]
	v_pk_mul_f32 v[220:221], v[66:67], v[166:167]
	v_pk_mul_f32 v[222:223], v[68:69], v[164:165]
	v_pk_mul_f32 v[224:225], v[70:71], v[166:167]
	v_pk_fma_f32 v[68:69], v[68:69], v[160:161], v[218:219] neg_lo:[0,0,1] neg_hi:[0,0,1]
	v_pk_fma_f32 v[70:71], v[70:71], v[162:163], v[220:221] neg_lo:[0,0,1] neg_hi:[0,0,1]
	v_pk_fma_f32 v[64:65], v[64:65], v[160:161], v[222:223]
	v_pk_fma_f32 v[66:67], v[66:67], v[162:163], v[224:225]
	v_cvt_pk_bf16_f32 v232, v68, v69
	v_cvt_pk_bf16_f32 v233, v70, v71
	v_cvt_pk_bf16_f32 v234, v64, v65
	v_cvt_pk_bf16_f32 v235, v66, v67
	global_store_dwordx2 v236, v[232:233], s[10:11] offset:0
	global_store_dwordx2 v236, v[234:235], s[10:11] offset:32
	s_waitcnt vmcnt(16)
	s_add_u32 s10, s12, 0x8000
	s_addc_u32 s11, s13, 0
	v_pk_mul_f32 v[218:219], v[56:57], v[172:173]
	v_pk_mul_f32 v[220:221], v[58:59], v[174:175]
	v_pk_mul_f32 v[222:223], v[60:61], v[172:173]
	v_pk_mul_f32 v[224:225], v[62:63], v[174:175]
	v_pk_fma_f32 v[60:61], v[60:61], v[168:169], v[218:219] neg_lo:[0,0,1] neg_hi:[0,0,1]
	v_pk_fma_f32 v[62:63], v[62:63], v[170:171], v[220:221] neg_lo:[0,0,1] neg_hi:[0,0,1]
	v_pk_fma_f32 v[56:57], v[56:57], v[168:169], v[222:223]
	v_pk_fma_f32 v[58:59], v[58:59], v[170:171], v[224:225]
	v_cvt_pk_bf16_f32 v228, v60, v61
	v_cvt_pk_bf16_f32 v229, v62, v63
	v_cvt_pk_bf16_f32 v230, v56, v57
	v_cvt_pk_bf16_f32 v231, v58, v59
	global_store_dwordx2 v236, v[228:229], s[10:11] offset:0
	global_store_dwordx2 v236, v[230:231], s[10:11] offset:32
	s_add_u32 s10, s12, 0xa8000
	s_addc_u32 s11, s13, 0
	v_pk_mul_f32 v[218:219], v[48:49], v[172:173]
	v_pk_mul_f32 v[220:221], v[50:51], v[174:175]
	v_pk_mul_f32 v[222:223], v[52:53], v[172:173]
	v_pk_mul_f32 v[224:225], v[54:55], v[174:175]
	v_pk_fma_f32 v[52:53], v[52:53], v[168:169], v[218:219] neg_lo:[0,0,1] neg_hi:[0,0,1]
	v_pk_fma_f32 v[54:55], v[54:55], v[170:171], v[220:221] neg_lo:[0,0,1] neg_hi:[0,0,1]
	v_pk_fma_f32 v[48:49], v[48:49], v[168:169], v[222:223]
	v_pk_fma_f32 v[50:51], v[50:51], v[170:171], v[224:225]
	v_cvt_pk_bf16_f32 v232, v52, v53
	v_cvt_pk_bf16_f32 v233, v54, v55
	v_cvt_pk_bf16_f32 v234, v48, v49
	v_cvt_pk_bf16_f32 v235, v50, v51
	global_store_dwordx2 v236, v[232:233], s[10:11] offset:0
	global_store_dwordx2 v236, v[234:235], s[10:11] offset:32
	s_add_u32 s10, s12, 0x9000
	s_addc_u32 s11, s13, 0
	v_pk_mul_f32 v[218:219], v[40:41], v[172:173]
	v_pk_mul_f32 v[220:221], v[42:43], v[174:175]
	v_pk_mul_f32 v[222:223], v[44:45], v[172:173]
	v_pk_mul_f32 v[224:225], v[46:47], v[174:175]
	v_pk_fma_f32 v[44:45], v[44:45], v[168:169], v[218:219] neg_lo:[0,0,1] neg_hi:[0,0,1]
	v_pk_fma_f32 v[46:47], v[46:47], v[170:171], v[220:221] neg_lo:[0,0,1] neg_hi:[0,0,1]
	v_pk_fma_f32 v[40:41], v[40:41], v[168:169], v[222:223]
	v_pk_fma_f32 v[42:43], v[42:43], v[170:171], v[224:225]
	v_cvt_pk_bf16_f32 v228, v44, v45
	v_cvt_pk_bf16_f32 v229, v46, v47
	v_cvt_pk_bf16_f32 v230, v40, v41
	v_cvt_pk_bf16_f32 v231, v42, v43
	global_store_dwordx2 v236, v[228:229], s[10:11] offset:0
	global_store_dwordx2 v236, v[230:231], s[10:11] offset:32
	s_add_u32 s10, s12, 0xa9000
	s_addc_u32 s11, s13, 0
	v_pk_mul_f32 v[218:219], v[32:33], v[172:173]
	v_pk_mul_f32 v[220:221], v[34:35], v[174:175]
	v_pk_mul_f32 v[222:223], v[36:37], v[172:173]
	v_pk_mul_f32 v[224:225], v[38:39], v[174:175]
	v_pk_fma_f32 v[36:37], v[36:37], v[168:169], v[218:219] neg_lo:[0,0,1] neg_hi:[0,0,1]
	v_pk_fma_f32 v[38:39], v[38:39], v[170:171], v[220:221] neg_lo:[0,0,1] neg_hi:[0,0,1]
	v_pk_fma_f32 v[32:33], v[32:33], v[168:169], v[222:223]
	v_pk_fma_f32 v[34:35], v[34:35], v[170:171], v[224:225]
	v_cvt_pk_bf16_f32 v232, v36, v37
	v_cvt_pk_bf16_f32 v233, v38, v39
	v_cvt_pk_bf16_f32 v234, v32, v33
	v_cvt_pk_bf16_f32 v235, v34, v35
	global_store_dwordx2 v236, v[232:233], s[10:11] offset:0
	global_store_dwordx2 v236, v[234:235], s[10:11] offset:32
	s_add_u32 s10, s12, 0xa000
	s_addc_u32 s11, s13, 0
	v_pk_mul_f32 v[218:219], v[24:25], v[172:173]
	v_pk_mul_f32 v[220:221], v[26:27], v[174:175]
	v_pk_mul_f32 v[222:223], v[28:29], v[172:173]
	v_pk_mul_f32 v[224:225], v[30:31], v[174:175]
	v_pk_fma_f32 v[28:29], v[28:29], v[168:169], v[218:219] neg_lo:[0,0,1] neg_hi:[0,0,1]
	v_pk_fma_f32 v[30:31], v[30:31], v[170:171], v[220:221] neg_lo:[0,0,1] neg_hi:[0,0,1]
	v_pk_fma_f32 v[24:25], v[24:25], v[168:169], v[222:223]
	v_pk_fma_f32 v[26:27], v[26:27], v[170:171], v[224:225]
	v_cvt_pk_bf16_f32 v228, v28, v29
	v_cvt_pk_bf16_f32 v229, v30, v31
	v_cvt_pk_bf16_f32 v230, v24, v25
	v_cvt_pk_bf16_f32 v231, v26, v27
	global_store_dwordx2 v236, v[228:229], s[10:11] offset:0
	global_store_dwordx2 v236, v[230:231], s[10:11] offset:32
	s_add_u32 s10, s12, 0xaa000
	s_addc_u32 s11, s13, 0
	v_pk_mul_f32 v[218:219], v[16:17], v[172:173]
	v_pk_mul_f32 v[220:221], v[18:19], v[174:175]
	v_pk_mul_f32 v[222:223], v[20:21], v[172:173]
	v_pk_mul_f32 v[224:225], v[22:23], v[174:175]
	v_pk_fma_f32 v[20:21], v[20:21], v[168:169], v[218:219] neg_lo:[0,0,1] neg_hi:[0,0,1]
	v_pk_fma_f32 v[22:23], v[22:23], v[170:171], v[220:221] neg_lo:[0,0,1] neg_hi:[0,0,1]
	v_pk_fma_f32 v[16:17], v[16:17], v[168:169], v[222:223]
	v_pk_fma_f32 v[18:19], v[18:19], v[170:171], v[224:225]
	v_cvt_pk_bf16_f32 v232, v20, v21
	v_cvt_pk_bf16_f32 v233, v22, v23
	v_cvt_pk_bf16_f32 v234, v16, v17
	v_cvt_pk_bf16_f32 v235, v18, v19
	global_store_dwordx2 v236, v[232:233], s[10:11] offset:0
	global_store_dwordx2 v236, v[234:235], s[10:11] offset:32
	s_add_u32 s10, s12, 0xb000
	s_addc_u32 s11, s13, 0
	v_pk_mul_f32 v[218:219], v[8:9], v[172:173]
	v_pk_mul_f32 v[220:221], v[10:11], v[174:175]
	v_pk_mul_f32 v[222:223], v[12:13], v[172:173]
	v_pk_mul_f32 v[224:225], v[14:15], v[174:175]
	v_pk_fma_f32 v[12:13], v[12:13], v[168:169], v[218:219] neg_lo:[0,0,1] neg_hi:[0,0,1]
	v_pk_fma_f32 v[14:15], v[14:15], v[170:171], v[220:221] neg_lo:[0,0,1] neg_hi:[0,0,1]
	v_pk_fma_f32 v[8:9], v[8:9], v[168:169], v[222:223]
	v_pk_fma_f32 v[10:11], v[10:11], v[170:171], v[224:225]
	v_cvt_pk_bf16_f32 v228, v12, v13
	v_cvt_pk_bf16_f32 v229, v14, v15
	v_cvt_pk_bf16_f32 v230, v8, v9
	v_cvt_pk_bf16_f32 v231, v10, v11
	global_store_dwordx2 v236, v[228:229], s[10:11] offset:0
	global_store_dwordx2 v236, v[230:231], s[10:11] offset:32
	s_add_u32 s10, s12, 0xab000
	s_addc_u32 s11, s13, 0
	v_pk_mul_f32 v[218:219], v[0:1], v[172:173]
	v_pk_mul_f32 v[220:221], v[2:3], v[174:175]
	v_pk_mul_f32 v[222:223], v[4:5], v[172:173]
	v_pk_mul_f32 v[224:225], v[6:7], v[174:175]
	v_pk_fma_f32 v[4:5], v[4:5], v[168:169], v[218:219] neg_lo:[0,0,1] neg_hi:[0,0,1]
	v_pk_fma_f32 v[6:7], v[6:7], v[170:171], v[220:221] neg_lo:[0,0,1] neg_hi:[0,0,1]
	v_pk_fma_f32 v[0:1], v[0:1], v[168:169], v[222:223]
	v_pk_fma_f32 v[2:3], v[2:3], v[170:171], v[224:225]
	v_cvt_pk_bf16_f32 v232, v4, v5
	v_cvt_pk_bf16_f32 v233, v6, v7
	v_cvt_pk_bf16_f32 v234, v0, v1
	v_cvt_pk_bf16_f32 v235, v2, v3
	global_store_dwordx2 v236, v[232:233], s[10:11] offset:0
	global_store_dwordx2 v236, v[234:235], s[10:11] offset:32
	s_branch .LBB0_141
.Lqk_k_l1:
	v_lshlrev_b32_e32 v238, 3, v186
	v_lshl_add_u32 v236, v217, 8, v238
	s_add_u32 s10, s30, 0x629a000
	s_addc_u32 s11, s31, 0
	v_lshlrev_b32_e32 v238, 4, v186
	v_lshl_add_u32 v241, v217, 6, v238
	s_add_u32 s8, s10, 0x1000
	s_addc_u32 s9, s11, 0
	global_load_dwordx4 v[160:163], v241, s[10:11] offset:0
	global_load_dwordx4 v[164:167], v241, s[8:9] offset:0
	global_load_dwordx4 v[168:171], v241, s[10:11] offset:1024
	global_load_dwordx4 v[172:175], v241, s[8:9] offset:1024
	global_load_dwordx4 v[176:179], v241, s[10:11] offset:2048
	global_load_dwordx4 v[180:183], v241, s[8:9] offset:2048
	global_load_dwordx4 v[184:187], v241, s[10:11] offset:3072
	global_load_dwordx4 v[188:191], v241, s[8:9] offset:3072
	s_add_i32 s35, s2, 0xffffffe0
	s_lshr_b32 s38, s35, 3
	s_lshl_b32 s38, s38, 2
	s_add_i32 s38, s38, s34
	s_mulk_i32 s38, 0xa00
	s_and_b32 s35, s35, 7
	s_lshl_b32 s35, s35, 8
	s_add_i32 s35, s35, s3
	s_add_i32 s35, s35, s38
	s_lshl_b32 s35, s35, 8
	s_lshl_b32 s38, s7, 1
	s_add_i32 s35, s35, s38
	s_add_u32 s12, s30, s35
	s_addc_u32 s13, s31, 0
	s_add_u32 s12, s12, 0xc2a4400
	s_addc_u32 s13, s13, 0
	s_waitcnt vmcnt(6)
	s_add_u32 s10, s12, 0x0
	s_addc_u32 s11, s13, 0
	v_pk_mul_f32 v[218:219], v[120:121], v[164:165]
	v_pk_mul_f32 v[220:221], v[122:123], v[166:167]
	v_pk_mul_f32 v[222:223], v[124:125], v[164:165]
	v_pk_mul_f32 v[224:225], v[126:127], v[166:167]
	v_pk_fma_f32 v[124:125], v[124:125], v[160:161], v[218:219] neg_lo:[0,0,1] neg_hi:[0,0,1]
	v_pk_fma_f32 v[126:127], v[126:127], v[162:163], v[220:221] neg_lo:[0,0,1] neg_hi:[0,0,1]
	v_pk_fma_f32 v[120:121], v[120:121], v[160:161], v[222:223]
	v_pk_fma_f32 v[122:123], v[122:123], v[162:163], v[224:225]
	v_cvt_pk_bf16_f32 v228, v124, v125
	v_cvt_pk_bf16_f32 v229, v126, v127
	v_cvt_pk_bf16_f32 v230, v120, v121
	v_cvt_pk_bf16_f32 v231, v122, v123
	global_store_dwordx2 v236, v[228:229], s[10:11] offset:0
	global_store_dwordx2 v236, v[230:231], s[10:11] offset:32
	s_add_u32 s10, s12, 0xa0000
	s_addc_u32 s11, s13, 0
	v_pk_mul_f32 v[218:219], v[112:113], v[164:165]
	v_pk_mul_f32 v[220:221], v[114:115], v[166:167]
	v_pk_mul_f32 v[222:223], v[116:117], v[164:165]
	v_pk_mul_f32 v[224:225], v[118:119], v[166:167]
	v_pk_fma_f32 v[116:117], v[116:117], v[160:161], v[218:219] neg_lo:[0,0,1] neg_hi:[0,0,1]
	v_pk_fma_f32 v[118:119], v[118:119], v[162:163], v[220:221] neg_lo:[0,0,1] neg_hi:[0,0,1]
	v_pk_fma_f32 v[112:113], v[112:113], v[160:161], v[222:223]
	v_pk_fma_f32 v[114:115], v[114:115], v[162:163], v[224:225]
	v_cvt_pk_bf16_f32 v232, v116, v117
	v_cvt_pk_bf16_f32 v233, v118, v119
	v_cvt_pk_bf16_f32 v234, v112, v113
	v_cvt_pk_bf16_f32 v235, v114, v115
	global_store_dwordx2 v236, v[232:233], s[10:11] offset:0
	global_store_dwordx2 v236, v[234:235], s[10:11] offset:32
	s_waitcnt vmcnt(8)
	s_add_u32 s10, s12, 0x1000
	s_addc_u32 s11, s13, 0
	v_pk_mul_f32 v[218:219], v[104:105], v[172:173]
	v_pk_mul_f32 v[220:221], v[106:107], v[174:175]
	v_pk_mul_f32 v[222:223], v[108:109], v[172:173]
	v_pk_mul_f32 v[224:225], v[110:111], v[174:175]
	v_pk_fma_f32 v[108:109], v[108:109], v[168:169], v[218:219] neg_lo:[0,0,1] neg_hi:[0,0,1]
	v_pk_fma_f32 v[110:111], v[110:111], v[170:171], v[220:221] neg_lo:[0,0,1] neg_hi:[0,0,1]
	v_pk_fma_f32 v[104:105], v[104:105], v[168:169], v[222:223]
	v_pk_fma_f32 v[106:107], v[106:107], v[170:171], v[224:225]
	v_cvt_pk_bf16_f32 v228, v108, v109
	v_cvt_pk_bf16_f32 v229, v110, v111
	v_cvt_pk_bf16_f32 v230, v104, v105
	v_cvt_pk_bf16_f32 v231, v106, v107
	global_store_dwordx2 v236, v[228:229], s[10:11] offset:0
	global_store_dwordx2 v236, v[230:231], s[10:11] offset:32
	s_add_u32 s10, s12, 0xa1000
	s_addc_u32 s11, s13, 0
	v_pk_mul_f32 v[218:219], v[96:97], v[172:173]
	v_pk_mul_f32 v[220:221], v[98:99], v[174:175]
	v_pk_mul_f32 v[222:223], v[100:101], v[172:173]
	v_pk_mul_f32 v[224:225], v[102:103], v[174:175]
	v_pk_fma_f32 v[100:101], v[100:101], v[168:169], v[218:219] neg_lo:[0,0,1] neg_hi:[0,0,1]
	v_pk_fma_f32 v[102:103], v[102:103], v[170:171], v[220:221] neg_lo:[0,0,1] neg_hi:[0,0,1]
	v_pk_fma_f32 v[96:97], v[96:97], v[168:169], v[222:223]
	v_pk_fma_f32 v[98:99], v[98:99], v[170:171], v[224:225]
	v_cvt_pk_bf16_f32 v232, v100, v101
	v_cvt_pk_bf16_f32 v233, v102, v103
	v_cvt_pk_bf16_f32 v234, v96, v97
	v_cvt_pk_bf16_f32 v235, v98, v99
	global_store_dwordx2 v236, v[232:233], s[10:11] offset:0
	global_store_dwordx2 v236, v[234:235], s[10:11] offset:32
	s_waitcnt vmcnt(10)
	s_add_u32 s10, s12, 0x2000
	s_addc_u32 s11, s13, 0
	v_pk_mul_f32 v[218:219], v[88:89], v[180:181]
	v_pk_mul_f32 v[220:221], v[90:91], v[182:183]
	v_pk_mul_f32 v[222:223], v[92:93], v[180:181]
	v_pk_mul_f32 v[224:225], v[94:95], v[182:183]
	v_pk_fma_f32 v[92:93], v[92:93], v[176:177], v[218:219] neg_lo:[0,0,1] neg_hi:[0,0,1]
	v_pk_fma_f32 v[94:95], v[94:95], v[178:179], v[220:221] neg_lo:[0,0,1] neg_hi:[0,0,1]
	v_pk_fma_f32 v[88:89], v[88:89], v[176:177], v[222:223]
	v_pk_fma_f32 v[90:91], v[90:91], v[178:179], v[224:225]
	v_cvt_pk_bf16_f32 v228, v92, v93
	v_cvt_pk_bf16_f32 v229, v94, v95
	v_cvt_pk_bf16_f32 v230, v88, v89
	v_cvt_pk_bf16_f32 v231, v90, v91
	global_store_dwordx2 v236, v[228:229], s[10:11] offset:0
	global_store_dwordx2 v236, v[230:231], s[10:11] offset:32
	s_add_u32 s10, s12, 0xa2000
	s_addc_u32 s11, s13, 0
	v_pk_mul_f32 v[218:219], v[80:81], v[180:181]
	v_pk_mul_f32 v[220:221], v[82:83], v[182:183]
	v_pk_mul_f32 v[222:223], v[84:85], v[180:181]
	v_pk_mul_f32 v[224:225], v[86:87], v[182:183]
	v_pk_fma_f32 v[84:85], v[84:85], v[176:177], v[218:219] neg_lo:[0,0,1] neg_hi:[0,0,1]
	v_pk_fma_f32 v[86:87], v[86:87], v[178:179], v[220:221] neg_lo:[0,0,1] neg_hi:[0,0,1]
	v_pk_fma_f32 v[80:81], v[80:81], v[176:177], v[222:223]
	v_pk_fma_f32 v[82:83], v[82:83], v[178:179], v[224:225]
	v_cvt_pk_bf16_f32 v232, v84, v85
	v_cvt_pk_bf16_f32 v233, v86, v87
	v_cvt_pk_bf16_f32 v234, v80, v81
	v_cvt_pk_bf16_f32 v235, v82, v83
	global_store_dwordx2 v236, v[232:233], s[10:11] offset:0
	global_store_dwordx2 v236, v[234:235], s[10:11] offset:32
	s_waitcnt vmcnt(12)
	s_add_u32 s10, s12, 0x3000
	s_addc_u32 s11, s13, 0
	v_pk_mul_f32 v[218:219], v[72:73], v[188:189]
	v_pk_mul_f32 v[220:221], v[74:75], v[190:191]
	v_pk_mul_f32 v[222:223], v[76:77], v[188:189]
	v_pk_mul_f32 v[224:225], v[78:79], v[190:191]
	v_pk_fma_f32 v[76:77], v[76:77], v[184:185], v[218:219] neg_lo:[0,0,1] neg_hi:[0,0,1]
	v_pk_fma_f32 v[78:79], v[78:79], v[186:187], v[220:221] neg_lo:[0,0,1] neg_hi:[0,0,1]
	v_pk_fma_f32 v[72:73], v[72:73], v[184:185], v[222:223]
	v_pk_fma_f32 v[74:75], v[74:75], v[186:187], v[224:225]
	v_cvt_pk_bf16_f32 v228, v76, v77
	v_cvt_pk_bf16_f32 v229, v78, v79
	v_cvt_pk_bf16_f32 v230, v72, v73
	v_cvt_pk_bf16_f32 v231, v74, v75
	global_store_dwordx2 v236, v[228:229], s[10:11] offset:0
	global_store_dwordx2 v236, v[230:231], s[10:11] offset:32
	s_add_u32 s10, s12, 0xa3000
	s_addc_u32 s11, s13, 0
	v_pk_mul_f32 v[218:219], v[64:65], v[188:189]
	v_pk_mul_f32 v[220:221], v[66:67], v[190:191]
	v_pk_mul_f32 v[222:223], v[68:69], v[188:189]
	v_pk_mul_f32 v[224:225], v[70:71], v[190:191]
	v_pk_fma_f32 v[68:69], v[68:69], v[184:185], v[218:219] neg_lo:[0,0,1] neg_hi:[0,0,1]
	v_pk_fma_f32 v[70:71], v[70:71], v[186:187], v[220:221] neg_lo:[0,0,1] neg_hi:[0,0,1]
	v_pk_fma_f32 v[64:65], v[64:65], v[184:185], v[222:223]
	v_pk_fma_f32 v[66:67], v[66:67], v[186:187], v[224:225]
	v_cvt_pk_bf16_f32 v232, v68, v69
	v_cvt_pk_bf16_f32 v233, v70, v71
	v_cvt_pk_bf16_f32 v234, v64, v65
	v_cvt_pk_bf16_f32 v235, v66, v67
	global_store_dwordx2 v236, v[232:233], s[10:11] offset:0
	global_store_dwordx2 v236, v[234:235], s[10:11] offset:32
	s_add_u32 s10, s12, 0x8000
	s_addc_u32 s11, s13, 0
	v_pk_mul_f32 v[218:219], v[56:57], v[164:165]
	v_pk_mul_f32 v[220:221], v[58:59], v[166:167]
	v_pk_mul_f32 v[222:223], v[60:61], v[164:165]
	v_pk_mul_f32 v[224:225], v[62:63], v[166:167]
	v_pk_fma_f32 v[60:61], v[60:61], v[160:161], v[218:219] neg_lo:[0,0,1] neg_hi:[0,0,1]
	v_pk_fma_f32 v[62:63], v[62:63], v[162:163], v[220:221] neg_lo:[0,0,1] neg_hi:[0,0,1]
	v_pk_fma_f32 v[56:57], v[56:57], v[160:161], v[222:223]
	v_pk_fma_f32 v[58:59], v[58:59], v[162:163], v[224:225]
	v_cvt_pk_bf16_f32 v228, v60, v61
	v_cvt_pk_bf16_f32 v229, v62, v63
	v_cvt_pk_bf16_f32 v230, v56, v57
	v_cvt_pk_bf16_f32 v231, v58, v59
	global_store_dwordx2 v236, v[228:229], s[10:11] offset:0
	global_store_dwordx2 v236, v[230:231], s[10:11] offset:32
	s_add_u32 s10, s12, 0xa8000
	s_addc_u32 s11, s13, 0
	v_pk_mul_f32 v[218:219], v[48:49], v[164:165]
	v_pk_mul_f32 v[220:221], v[50:51], v[166:167]
	v_pk_mul_f32 v[222:223], v[52:53], v[164:165]
	v_pk_mul_f32 v[224:225], v[54:55], v[166:167]
	v_pk_fma_f32 v[52:53], v[52:53], v[160:161], v[218:219] neg_lo:[0,0,1] neg_hi:[0,0,1]
	v_pk_fma_f32 v[54:55], v[54:55], v[162:163], v[220:221] neg_lo:[0,0,1] neg_hi:[0,0,1]
	v_pk_fma_f32 v[48:49], v[48:49], v[160:161], v[222:223]
	v_pk_fma_f32 v[50:51], v[50:51], v[162:163], v[224:225]
	v_cvt_pk_bf16_f32 v232, v52, v53
	v_cvt_pk_bf16_f32 v233, v54, v55
	v_cvt_pk_bf16_f32 v234, v48, v49
	v_cvt_pk_bf16_f32 v235, v50, v51
	global_store_dwordx2 v236, v[232:233], s[10:11] offset:0
	global_store_dwordx2 v236, v[234:235], s[10:11] offset:32
	s_add_u32 s10, s12, 0x9000
	s_addc_u32 s11, s13, 0
	v_pk_mul_f32 v[218:219], v[40:41], v[172:173]
	v_pk_mul_f32 v[220:221], v[42:43], v[174:175]
	v_pk_mul_f32 v[222:223], v[44:45], v[172:173]
	v_pk_mul_f32 v[224:225], v[46:47], v[174:175]
	v_pk_fma_f32 v[44:45], v[44:45], v[168:169], v[218:219] neg_lo:[0,0,1] neg_hi:[0,0,1]
	v_pk_fma_f32 v[46:47], v[46:47], v[170:171], v[220:221] neg_lo:[0,0,1] neg_hi:[0,0,1]
	v_pk_fma_f32 v[40:41], v[40:41], v[168:169], v[222:223]
	v_pk_fma_f32 v[42:43], v[42:43], v[170:171], v[224:225]
	v_cvt_pk_bf16_f32 v228, v44, v45
	v_cvt_pk_bf16_f32 v229, v46, v47
	v_cvt_pk_bf16_f32 v230, v40, v41
	v_cvt_pk_bf16_f32 v231, v42, v43
	global_store_dwordx2 v236, v[228:229], s[10:11] offset:0
	global_store_dwordx2 v236, v[230:231], s[10:11] offset:32
	s_add_u32 s10, s12, 0xa9000
	s_addc_u32 s11, s13, 0
	v_pk_mul_f32 v[218:219], v[32:33], v[172:173]
	v_pk_mul_f32 v[220:221], v[34:35], v[174:175]
	v_pk_mul_f32 v[222:223], v[36:37], v[172:173]
	v_pk_mul_f32 v[224:225], v[38:39], v[174:175]
	v_pk_fma_f32 v[36:37], v[36:37], v[168:169], v[218:219] neg_lo:[0,0,1] neg_hi:[0,0,1]
	v_pk_fma_f32 v[38:39], v[38:39], v[170:171], v[220:221] neg_lo:[0,0,1] neg_hi:[0,0,1]
	v_pk_fma_f32 v[32:33], v[32:33], v[168:169], v[222:223]
	v_pk_fma_f32 v[34:35], v[34:35], v[170:171], v[224:225]
	v_cvt_pk_bf16_f32 v232, v36, v37
	v_cvt_pk_bf16_f32 v233, v38, v39
	v_cvt_pk_bf16_f32 v234, v32, v33
	v_cvt_pk_bf16_f32 v235, v34, v35
	global_store_dwordx2 v236, v[232:233], s[10:11] offset:0
	global_store_dwordx2 v236, v[234:235], s[10:11] offset:32
	s_add_u32 s10, s12, 0xa000
	s_addc_u32 s11, s13, 0
	v_pk_mul_f32 v[218:219], v[24:25], v[180:181]
	v_pk_mul_f32 v[220:221], v[26:27], v[182:183]
	v_pk_mul_f32 v[222:223], v[28:29], v[180:181]
	v_pk_mul_f32 v[224:225], v[30:31], v[182:183]
	v_pk_fma_f32 v[28:29], v[28:29], v[176:177], v[218:219] neg_lo:[0,0,1] neg_hi:[0,0,1]
	v_pk_fma_f32 v[30:31], v[30:31], v[178:179], v[220:221] neg_lo:[0,0,1] neg_hi:[0,0,1]
	v_pk_fma_f32 v[24:25], v[24:25], v[176:177], v[222:223]
	v_pk_fma_f32 v[26:27], v[26:27], v[178:179], v[224:225]
	v_cvt_pk_bf16_f32 v228, v28, v29
	v_cvt_pk_bf16_f32 v229, v30, v31
	v_cvt_pk_bf16_f32 v230, v24, v25
	v_cvt_pk_bf16_f32 v231, v26, v27
	global_store_dwordx2 v236, v[228:229], s[10:11] offset:0
	global_store_dwordx2 v236, v[230:231], s[10:11] offset:32
	s_add_u32 s10, s12, 0xaa000
	s_addc_u32 s11, s13, 0
	v_pk_mul_f32 v[218:219], v[16:17], v[180:181]
	v_pk_mul_f32 v[220:221], v[18:19], v[182:183]
	v_pk_mul_f32 v[222:223], v[20:21], v[180:181]
	v_pk_mul_f32 v[224:225], v[22:23], v[182:183]
	v_pk_fma_f32 v[20:21], v[20:21], v[176:177], v[218:219] neg_lo:[0,0,1] neg_hi:[0,0,1]
	v_pk_fma_f32 v[22:23], v[22:23], v[178:179], v[220:221] neg_lo:[0,0,1] neg_hi:[0,0,1]
	v_pk_fma_f32 v[16:17], v[16:17], v[176:177], v[222:223]
	v_pk_fma_f32 v[18:19], v[18:19], v[178:179], v[224:225]
	v_cvt_pk_bf16_f32 v232, v20, v21
	v_cvt_pk_bf16_f32 v233, v22, v23
	v_cvt_pk_bf16_f32 v234, v16, v17
	v_cvt_pk_bf16_f32 v235, v18, v19
	global_store_dwordx2 v236, v[232:233], s[10:11] offset:0
	global_store_dwordx2 v236, v[234:235], s[10:11] offset:32
	s_add_u32 s10, s12, 0xb000
	s_addc_u32 s11, s13, 0
	v_pk_mul_f32 v[218:219], v[8:9], v[188:189]
	v_pk_mul_f32 v[220:221], v[10:11], v[190:191]
	v_pk_mul_f32 v[222:223], v[12:13], v[188:189]
	v_pk_mul_f32 v[224:225], v[14:15], v[190:191]
	v_pk_fma_f32 v[12:13], v[12:13], v[184:185], v[218:219] neg_lo:[0,0,1] neg_hi:[0,0,1]
	v_pk_fma_f32 v[14:15], v[14:15], v[186:187], v[220:221] neg_lo:[0,0,1] neg_hi:[0,0,1]
	v_pk_fma_f32 v[8:9], v[8:9], v[184:185], v[222:223]
	v_pk_fma_f32 v[10:11], v[10:11], v[186:187], v[224:225]
	v_cvt_pk_bf16_f32 v228, v12, v13
	v_cvt_pk_bf16_f32 v229, v14, v15
	v_cvt_pk_bf16_f32 v230, v8, v9
	v_cvt_pk_bf16_f32 v231, v10, v11
	global_store_dwordx2 v236, v[228:229], s[10:11] offset:0
	global_store_dwordx2 v236, v[230:231], s[10:11] offset:32
	s_add_u32 s10, s12, 0xab000
	s_addc_u32 s11, s13, 0
	v_pk_mul_f32 v[218:219], v[0:1], v[188:189]
	v_pk_mul_f32 v[220:221], v[2:3], v[190:191]
	v_pk_mul_f32 v[222:223], v[4:5], v[188:189]
	v_pk_mul_f32 v[224:225], v[6:7], v[190:191]
	v_pk_fma_f32 v[4:5], v[4:5], v[184:185], v[218:219] neg_lo:[0,0,1] neg_hi:[0,0,1]
	v_pk_fma_f32 v[6:7], v[6:7], v[186:187], v[220:221] neg_lo:[0,0,1] neg_hi:[0,0,1]
	v_pk_fma_f32 v[0:1], v[0:1], v[184:185], v[222:223]
	v_pk_fma_f32 v[2:3], v[2:3], v[186:187], v[224:225]
	v_cvt_pk_bf16_f32 v232, v4, v5
	v_cvt_pk_bf16_f32 v233, v6, v7
	v_cvt_pk_bf16_f32 v234, v0, v1
	v_cvt_pk_bf16_f32 v235, v2, v3
	global_store_dwordx2 v236, v[232:233], s[10:11] offset:0
	global_store_dwordx2 v236, v[234:235], s[10:11] offset:32
	s_branch .LBB0_141
.Lqk_k_c:
	v_lshlrev_b32_e32 v238, 3, v186
	v_lshl_add_u32 v236, v217, 8, v238
	v_lshlrev_b32_e32 v238, 4, v186
	v_lshl_add_u32 v237, v217, 11, v238
	s_lshl_b32 s35, s2, 2
	s_add_i32 s35, s35, s34
	s_lshl_b32 s35, s35, 8
	s_add_i32 s35, s35, s3
	s_lshl_b32 s35, s35, 8
	s_lshl_b32 s38, s7, 1
	s_add_i32 s35, s35, s38
	s_add_u32 s12, s30, s35
	s_addc_u32 s13, s31, 0
	s_add_u32 s12, s12, 0xb2a4400
	s_addc_u32 s13, s13, 0
	s_lshl_b32 s35, s2, 1
	s_add_i32 s35, s35, s40
	s_lshl_b32 s35, s35, 8
	s_add_i32 s35, s35, s3
	s_lshl_b32 s35, s35, 11
	s_lshl_b32 s38, s34, 7
	s_add_i32 s38, s38, s7
	s_lshl_b32 s38, s38, 2
	s_add_i32 s35, s35, s38
	s_add_u32 s26, s28, s35
	s_addc_u32 s27, s29, 0
	s_add_u32 s26, s26, 0x4000000
	s_addc_u32 s27, s27, 0
	s_add_u32 s10, s12, 0x0
	s_addc_u32 s11, s13, 0
	s_add_u32 s8, s26, 0x0
	s_addc_u32 s9, s27, 0
	global_store_dwordx4 v237, v[124:127], s[8:9] offset:0
	global_store_dwordx4 v237, v[120:123], s[8:9] offset:64
	v_cvt_pk_bf16_f32 v228, v124, v125
	v_cvt_pk_bf16_f32 v229, v126, v127
	v_cvt_pk_bf16_f32 v230, v120, v121
	v_cvt_pk_bf16_f32 v231, v122, v123
	global_store_dwordx2 v236, v[228:229], s[10:11] offset:0
	global_store_dwordx2 v236, v[230:231], s[10:11] offset:32
	s_add_u32 s10, s12, 0x10000
	s_addc_u32 s11, s13, 0
	global_store_dwordx4 v237, v[116:119], s[8:9] offset:512
	global_store_dwordx4 v237, v[112:115], s[8:9] offset:576
	v_cvt_pk_bf16_f32 v232, v116, v117
	v_cvt_pk_bf16_f32 v233, v118, v119
	v_cvt_pk_bf16_f32 v234, v112, v113
	v_cvt_pk_bf16_f32 v235, v114, v115
	global_store_dwordx2 v236, v[232:233], s[10:11] offset:0
	global_store_dwordx2 v236, v[234:235], s[10:11] offset:32
	s_add_u32 s10, s12, 0x1000
	s_addc_u32 s11, s13, 0
	s_add_u32 s8, s26, 0x8000
	s_addc_u32 s9, s27, 0
	global_store_dwordx4 v237, v[108:111], s[8:9] offset:0
	global_store_dwordx4 v237, v[104:107], s[8:9] offset:64
	v_cvt_pk_bf16_f32 v228, v108, v109
	v_cvt_pk_bf16_f32 v229, v110, v111
	v_cvt_pk_bf16_f32 v230, v104, v105
	v_cvt_pk_bf16_f32 v231, v106, v107
	global_store_dwordx2 v236, v[228:229], s[10:11] offset:0
	global_store_dwordx2 v236, v[230:231], s[10:11] offset:32
	s_add_u32 s10, s12, 0x11000
	s_addc_u32 s11, s13, 0
	global_store_dwordx4 v237, v[100:103], s[8:9] offset:512
	global_store_dwordx4 v237, v[96:99], s[8:9] offset:576
	v_cvt_pk_bf16_f32 v232, v100, v101
	v_cvt_pk_bf16_f32 v233, v102, v103
	v_cvt_pk_bf16_f32 v234, v96, v97
	v_cvt_pk_bf16_f32 v235, v98, v99
	global_store_dwordx2 v236, v[232:233], s[10:11] offset:0
	global_store_dwordx2 v236, v[234:235], s[10:11] offset:32
	s_add_u32 s10, s12, 0x2000
	s_addc_u32 s11, s13, 0
	s_add_u32 s8, s26, 0x10000
	s_addc_u32 s9, s27, 0
	global_store_dwordx4 v237, v[92:95], s[8:9] offset:0
	global_store_dwordx4 v237, v[88:91], s[8:9] offset:64
	v_cvt_pk_bf16_f32 v228, v92, v93
	v_cvt_pk_bf16_f32 v229, v94, v95
	v_cvt_pk_bf16_f32 v230, v88, v89
	v_cvt_pk_bf16_f32 v231, v90, v91
	global_store_dwordx2 v236, v[228:229], s[10:11] offset:0
	global_store_dwordx2 v236, v[230:231], s[10:11] offset:32
	s_add_u32 s10, s12, 0x12000
	s_addc_u32 s11, s13, 0
	global_store_dwordx4 v237, v[84:87], s[8:9] offset:512
	global_store_dwordx4 v237, v[80:83], s[8:9] offset:576
	v_cvt_pk_bf16_f32 v232, v84, v85
	v_cvt_pk_bf16_f32 v233, v86, v87
	v_cvt_pk_bf16_f32 v234, v80, v81
	v_cvt_pk_bf16_f32 v235, v82, v83
	global_store_dwordx2 v236, v[232:233], s[10:11] offset:0
	global_store_dwordx2 v236, v[234:235], s[10:11] offset:32
	s_add_u32 s10, s12, 0x3000
	s_addc_u32 s11, s13, 0
	s_add_u32 s8, s26, 0x18000
	s_addc_u32 s9, s27, 0
	global_store_dwordx4 v237, v[76:79], s[8:9] offset:0
	global_store_dwordx4 v237, v[72:75], s[8:9] offset:64
	v_cvt_pk_bf16_f32 v228, v76, v77
	v_cvt_pk_bf16_f32 v229, v78, v79
	v_cvt_pk_bf16_f32 v230, v72, v73
	v_cvt_pk_bf16_f32 v231, v74, v75
	global_store_dwordx2 v236, v[228:229], s[10:11] offset:0
	global_store_dwordx2 v236, v[230:231], s[10:11] offset:32
	s_add_u32 s10, s12, 0x13000
	s_addc_u32 s11, s13, 0
	global_store_dwordx4 v237, v[68:71], s[8:9] offset:512
	global_store_dwordx4 v237, v[64:67], s[8:9] offset:576
	v_cvt_pk_bf16_f32 v232, v68, v69
	v_cvt_pk_bf16_f32 v233, v70, v71
	v_cvt_pk_bf16_f32 v234, v64, v65
	v_cvt_pk_bf16_f32 v235, v66, v67
	global_store_dwordx2 v236, v[232:233], s[10:11] offset:0
	global_store_dwordx2 v236, v[234:235], s[10:11] offset:32
	s_add_u32 s10, s12, 0x8000
	s_addc_u32 s11, s13, 0
	s_add_u32 s8, s26, 0x40000
	s_addc_u32 s9, s27, 0
	global_store_dwordx4 v237, v[60:63], s[8:9] offset:0
	global_store_dwordx4 v237, v[56:59], s[8:9] offset:64
	v_cvt_pk_bf16_f32 v228, v60, v61
	v_cvt_pk_bf16_f32 v229, v62, v63
	v_cvt_pk_bf16_f32 v230, v56, v57
	v_cvt_pk_bf16_f32 v231, v58, v59
	global_store_dwordx2 v236, v[228:229], s[10:11] offset:0
	global_store_dwordx2 v236, v[230:231], s[10:11] offset:32
	s_add_u32 s10, s12, 0x18000
	s_addc_u32 s11, s13, 0
	global_store_dwordx4 v237, v[52:55], s[8:9] offset:512
	global_store_dwordx4 v237, v[48:51], s[8:9] offset:576
	v_cvt_pk_bf16_f32 v232, v52, v53
	v_cvt_pk_bf16_f32 v233, v54, v55
	v_cvt_pk_bf16_f32 v234, v48, v49
	v_cvt_pk_bf16_f32 v235, v50, v51
	global_store_dwordx2 v236, v[232:233], s[10:11] offset:0
	global_store_dwordx2 v236, v[234:235], s[10:11] offset:32
	s_add_u32 s10, s12, 0x9000
	s_addc_u32 s11, s13, 0
	s_add_u32 s8, s26, 0x48000
	s_addc_u32 s9, s27, 0
	global_store_dwordx4 v237, v[44:47], s[8:9] offset:0
	global_store_dwordx4 v237, v[40:43], s[8:9] offset:64
	v_cvt_pk_bf16_f32 v228, v44, v45
	v_cvt_pk_bf16_f32 v229, v46, v47
	v_cvt_pk_bf16_f32 v230, v40, v41
	v_cvt_pk_bf16_f32 v231, v42, v43
	global_store_dwordx2 v236, v[228:229], s[10:11] offset:0
	global_store_dwordx2 v236, v[230:231], s[10:11] offset:32
	s_add_u32 s10, s12, 0x19000
	s_addc_u32 s11, s13, 0
	global_store_dwordx4 v237, v[36:39], s[8:9] offset:512
	global_store_dwordx4 v237, v[32:35], s[8:9] offset:576
	v_cvt_pk_bf16_f32 v232, v36, v37
	v_cvt_pk_bf16_f32 v233, v38, v39
	v_cvt_pk_bf16_f32 v234, v32, v33
	v_cvt_pk_bf16_f32 v235, v34, v35
	global_store_dwordx2 v236, v[232:233], s[10:11] offset:0
	global_store_dwordx2 v236, v[234:235], s[10:11] offset:32
	s_add_u32 s10, s12, 0xa000
	s_addc_u32 s11, s13, 0
	s_add_u32 s8, s26, 0x50000
	s_addc_u32 s9, s27, 0
	global_store_dwordx4 v237, v[28:31], s[8:9] offset:0
	global_store_dwordx4 v237, v[24:27], s[8:9] offset:64
	v_cvt_pk_bf16_f32 v228, v28, v29
	v_cvt_pk_bf16_f32 v229, v30, v31
	v_cvt_pk_bf16_f32 v230, v24, v25
	v_cvt_pk_bf16_f32 v231, v26, v27
	global_store_dwordx2 v236, v[228:229], s[10:11] offset:0
	global_store_dwordx2 v236, v[230:231], s[10:11] offset:32
	s_add_u32 s10, s12, 0x1a000
	s_addc_u32 s11, s13, 0
	global_store_dwordx4 v237, v[20:23], s[8:9] offset:512
	global_store_dwordx4 v237, v[16:19], s[8:9] offset:576
	v_cvt_pk_bf16_f32 v232, v20, v21
	v_cvt_pk_bf16_f32 v233, v22, v23
	v_cvt_pk_bf16_f32 v234, v16, v17
	v_cvt_pk_bf16_f32 v235, v18, v19
	global_store_dwordx2 v236, v[232:233], s[10:11] offset:0
	global_store_dwordx2 v236, v[234:235], s[10:11] offset:32
	s_add_u32 s10, s12, 0xb000
	s_addc_u32 s11, s13, 0
	s_add_u32 s8, s26, 0x58000
	s_addc_u32 s9, s27, 0
	global_store_dwordx4 v237, v[12:15], s[8:9] offset:0
	global_store_dwordx4 v237, v[8:11], s[8:9] offset:64
	v_cvt_pk_bf16_f32 v228, v12, v13
	v_cvt_pk_bf16_f32 v229, v14, v15
	v_cvt_pk_bf16_f32 v230, v8, v9
	v_cvt_pk_bf16_f32 v231, v10, v11
	global_store_dwordx2 v236, v[228:229], s[10:11] offset:0
	global_store_dwordx2 v236, v[230:231], s[10:11] offset:32
	s_add_u32 s10, s12, 0x1b000
	s_addc_u32 s11, s13, 0
	global_store_dwordx4 v237, v[4:7], s[8:9] offset:512
	global_store_dwordx4 v237, v[0:3], s[8:9] offset:576
	v_cvt_pk_bf16_f32 v232, v4, v5
	v_cvt_pk_bf16_f32 v233, v6, v7
	v_cvt_pk_bf16_f32 v234, v0, v1
	v_cvt_pk_bf16_f32 v235, v2, v3
	global_store_dwordx2 v236, v[232:233], s[10:11] offset:0
	global_store_dwordx2 v236, v[234:235], s[10:11] offset:32
	s_branch .LBB0_141
